# combo13 = combo12 + attention-tile, memory-KV GEMM and conversion loop heads aligned to 64 bytes
# baseline (speedup 1.0000x reference)
; __device__ __forceinline__ void stage_kv_load(u32x4 (&kr)[8], u32x4 (&vr)[8], const bf16_t* Kg, int kpitch, const bf16_t* Vtg, int tid) {
; #pragma unroll
;     for (int i = 0; i < 8; ++i) { const int c = tid + 512 * i, row = c >> 4, ch = c & 15; kr[i] = *(const u32x4*)(Kg + (size_t)row * kpitch + ch * 8); }
; #pragma unroll
;     for (int i = 0; i < 8; ++i) { const int c = tid + 512 * i, row = c >> 5, ch = c & 31; vr[i] = *(const u32x4*)(Vtg + (size_t)row * 256 + ch * 8); }
; }
; __global__ void __launch_bounds__(512, 2) mk_fwd(Args a) {
;     ...
;                     TID_LOCALS
;                     const int h = it & 7, b = it >> 3;
;                     u32x4 kr[8], vr[8];
;                     stage_kv_load(kr, vr, PROJ + (size_t)(256 * b) * INW + 1024 + 128 * h, INW, VT + (size_t)(h * 64 + b) * 128 * 256, tid);
;                     const int qi = 32 * wave + r32, tok = 256 * b + qi;
;                     const bf16_t* qrow = PROJ + (size_t)tok * INW + 128 * h + 8 * hi;
;                     bf16x8 qf[8];
; #pragma unroll
;                     for (int d0 = 0; d0 < 8; ++d0) qf[d0] = *(const bf16x8*)(qrow + 16 * d0);
.LBB0_22:
	s_ashr_i32 s14, s7, 3
	s_and_b32 s15, s7, 7
	s_lshl_b32 s18, s14, 8
	s_mul_i32 s0, s14, 0x280000
	s_mul_hi_i32 s1, s18, 0x2800
	s_add_u32 s0, s72, s0
	v_mov_b32_e32 v163, v232
	s_addc_u32 s1, s73, s1
	s_lshl_b32 s20, s15, 7
	s_lshl_b32 s74, s15, 8
	s_add_u32 s0, s0, s74
	v_lshlrev_b32_e32 v32, 4, v163
	s_addc_u32 s1, s1, 0
	s_lshl_b32 s15, s15, 6
	v_and_b32_e32 v128, 0xf0, v32
	v_add_u32_e32 v34, 0x200, v163
	s_add_i32 s16, s15, s14
	v_lshl_add_u64 v[24:25], s[0:1], 0, v[128:129]
	v_ashrrev_i32_e32 v86, 4, v163
	s_movk_i32 s15, 0x2800
	v_ashrrev_i32_e32 v88, 4, v34
	s_waitcnt lgkmcnt(0)
	v_mad_i64_i32 v[0:1], s[0:1], v86, s15, v[24:25]
	v_mad_i64_i32 v[4:5], s[0:1], v88, s15, v[24:25]
	v_add_u32_e32 v40, 0x400, v163
	v_add_u32_e32 v42, 0x600, v163
	flat_load_dwordx4 v[0:3], v[0:1] offset:2048
	s_nop 0
	flat_load_dwordx4 v[4:7], v[4:5] offset:2048
	v_ashrrev_i32_e32 v89, 4, v40
	v_ashrrev_i32_e32 v90, 4, v42
	v_mad_i64_i32 v[8:9], s[0:1], v89, s15, v[24:25]
	v_mad_i64_i32 v[12:13], s[0:1], v90, s15, v[24:25]
	v_add_u32_e32 v48, 0x800, v163
	v_add_u32_e32 v50, 0xa00, v163
	flat_load_dwordx4 v[8:11], v[8:9] offset:2048
	s_nop 0
	flat_load_dwordx4 v[12:15], v[12:13] offset:2048
	v_ashrrev_i32_e32 v91, 4, v48
	v_ashrrev_i32_e32 v92, 4, v50
	s_ashr_i32 s17, s16, 31
	v_mad_i64_i32 v[16:17], s[0:1], v91, s15, v[24:25]
	v_mad_i64_i32 v[20:21], s[0:1], v92, s15, v[24:25]
	v_add_u32_e32 v56, 0xc00, v163
	v_add_u32_e32 v62, 0xe00, v163
	s_lshl_b64 s[16:17], s[16:17], 16
	flat_load_dwordx4 v[16:19], v[16:17] offset:2048
	s_nop 0
	flat_load_dwordx4 v[20:23], v[20:21] offset:2048
	v_ashrrev_i32_e32 v93, 4, v56
	v_ashrrev_i32_e32 v94, 4, v62
	s_add_u32 s16, s96, s16
	v_mad_i64_i32 v[26:27], s[0:1], v93, s15, v[24:25]
	v_mad_i64_i32 v[28:29], s[0:1], v94, s15, v[24:25]
	v_ashrrev_i32_e32 v66, 5, v163
	v_ashrrev_i32_e32 v68, 5, v34
	s_addc_u32 s17, s97, s17
	flat_load_dwordx4 v[24:27], v[26:27] offset:2048
	s_nop 0
	flat_load_dwordx4 v[28:31], v[28:29] offset:2048
	v_and_b32_e32 v64, 0x1f0, v32
	v_mov_b32_e32 v65, v129
	v_ashrrev_i32_e32 v67, 31, v66
	v_ashrrev_i32_e32 v69, 31, v68
	v_readfirstlane_b32 s0, v163
	v_lshl_add_u64 v[60:61], s[16:17], 0, v[64:65]
	v_lshlrev_b64 v[32:33], 9, v[66:67]
	v_lshlrev_b64 v[34:35], 9, v[68:69]
	v_ashrrev_i32_e32 v70, 5, v40
	v_ashrrev_i32_e32 v72, 5, v42
	s_ashr_i32 s0, s0, 1
	v_lshl_add_u64 v[32:33], v[60:61], 0, v[32:33]
	v_lshl_add_u64 v[36:37], v[60:61], 0, v[34:35]
	v_ashrrev_i32_e32 v71, 31, v70
	v_ashrrev_i32_e32 v73, 31, v72
	v_mov_b32_e32 v67, s0
	s_movk_i32 s0, 0xffe0
	global_load_dwordx4 v[32:35], v[32:33], off
	s_nop 0
	global_load_dwordx4 v[36:39], v[36:37], off
	v_lshlrev_b64 v[40:41], 9, v[70:71]
	v_lshlrev_b64 v[42:43], 9, v[72:73]
	v_ashrrev_i32_e32 v74, 5, v48
	v_ashrrev_i32_e32 v76, 5, v50
	v_bfi_b32 v167, s0, v67, v163
	v_lshl_add_u64 v[40:41], v[60:61], 0, v[40:41]
	v_lshl_add_u64 v[44:45], v[60:61], 0, v[42:43]
	v_ashrrev_i32_e32 v75, 31, v74
	v_ashrrev_i32_e32 v77, 31, v76
	v_ashrrev_i32_e32 v78, 5, v56
	v_ashrrev_i32_e32 v80, 5, v62
	v_add_u32_e32 v164, s18, v167
	v_mov_b64_e32 v[82:83], s[72:73]
	global_load_dwordx4 v[40:43], v[40:41], off
	s_nop 0
	global_load_dwordx4 v[44:47], v[44:45], off
	v_lshlrev_b64 v[48:49], 9, v[74:75]
	v_lshlrev_b64 v[50:51], 9, v[76:77]
	v_ashrrev_i32_e32 v79, 31, v78
	v_ashrrev_i32_e32 v81, 31, v80
	v_bfe_u32 v65, v163, 5, 1
	v_mad_i64_i32 v[82:83], s[0:1], v164, s15, v[82:83]
	v_lshl_add_u64 v[48:49], v[60:61], 0, v[48:49]
	v_lshl_add_u64 v[52:53], v[60:61], 0, v[50:51]
	v_lshlrev_b64 v[56:57], 9, v[78:79]
	v_lshlrev_b64 v[62:63], 9, v[80:81]
	v_lshl_add_u64 v[82:83], v[82:83], 0, s[74:75]
	v_lshlrev_b32_e32 v84, 4, v65
	v_mov_b32_e32 v85, v129
	global_load_dwordx4 v[48:51], v[48:49], off
	s_nop 0
	global_load_dwordx4 v[52:55], v[52:53], off
	v_lshl_add_u64 v[56:57], v[60:61], 0, v[56:57]
	v_lshl_add_u64 v[60:61], v[60:61], 0, v[62:63]
	v_lshl_add_u64 v[82:83], v[82:83], 0, v[84:85]
	global_load_dwordx4 v[56:59], v[56:57], off
	v_readlane_b32 s16, v254, 28
	global_load_dwordx4 v[60:63], v[60:61], off
	s_nop 0
	flat_load_dwordx4 v[130:133], v[82:83]
	flat_load_dwordx4 v[134:137], v[82:83] offset:32
	flat_load_dwordx4 v[138:141], v[82:83] offset:64
	flat_load_dwordx4 v[142:145], v[82:83] offset:96
	flat_load_dwordx4 v[146:149], v[82:83] offset:128
	flat_load_dwordx4 v[150:153], v[82:83] offset:160
	flat_load_dwordx4 v[154:157], v[82:83] offset:192
	flat_load_dwordx4 v[158:161], v[82:83] offset:224
	v_add_u32_e32 v82, 0, v128
	v_mad_u64_u32 v[86:87], s[0:1], v86, s86, v[82:83]
	s_waitcnt vmcnt(0) lgkmcnt(0)
; #define LAS __attribute__((address_space(3)))
; __device__ __forceinline__ void stage_kv_store(LAS unsigned char* lds, const u32x4 (&kr)[8], const u32x4 (&vr)[8], int tid) {
; #pragma unroll
;     for (int i = 0; i < 8; ++i) { const int c = tid + 512 * i, row = c >> 4, ch = c & 15; *(LAS u32x4*)(lds + LDS_KS + row * KS_STRIDE + ch * 16) = kr[i]; }
; #pragma unroll
;     for (int i = 0; i < 8; ++i) { const int c = tid + 512 * i, row = c >> 5, ch = c & 31; *(LAS u32x4*)(lds + LDS_VT + row * VT_STRIDE + ch * 16) = vr[i]; }
; }
; __global__ void __launch_bounds__(512, 2) mk_fwd(Args a) {
;     ...
;                     stage_kv_store(lds, kr, vr, tid);
;                     __syncthreads();
;                     f32x16 O[4]; float m2, ll;
;                     attn_tile<true>(lds + LDS_KS, lds + LDS_VT, qf, qi, r32, hi, O, m2, ll);
	ds_write_b128 v86, v[0:3]
	v_mad_u64_u32 v[0:1], s[0:1], v88, s86, v[82:83]
	ds_write_b128 v0, v[4:7]
	v_mad_u64_u32 v[0:1], s[0:1], v89, s86, v[82:83]
	ds_write_b128 v0, v[8:11]
	v_mad_u64_u32 v[0:1], s[0:1], v90, s86, v[82:83]
	ds_write_b128 v0, v[12:15]
	v_mad_u64_u32 v[0:1], s[0:1], v91, s86, v[82:83]
	ds_write_b128 v0, v[16:19]
	v_mad_u64_u32 v[0:1], s[0:1], v92, s86, v[82:83]
	ds_write_b128 v0, v[20:23]
	v_mad_u64_u32 v[0:1], s[0:1], v93, s86, v[82:83]
	s_movk_i32 s15, 0x210
	v_and_b32_e32 v166, 31, v163
	v_lshlrev_b32_e32 v162, 3, v65
	ds_write_b128 v0, v[24:27]
	v_mad_u64_u32 v[0:1], s[0:1], v94, s86, v[82:83]
	ds_write_b128 v0, v[28:31]
	v_add_u32_e32 v0, s16, v64
	v_mad_u64_u32 v[2:3], s[0:1], v66, s15, v[0:1]
	v_mov_b32_e32 v171, 0
	v_ashrrev_i32_e32 v165, 31, v164
	v_add_u32_e32 v128, 0, v84
	v_lshlrev_b32_e32 v168, 2, v65
	v_mov_b32_e32 v4, v171
	v_mov_b32_e32 v5, v171
	v_mov_b32_e32 v6, v171
	v_mov_b32_e32 v7, v171
	v_mov_b32_e32 v8, v171
	v_mov_b32_e32 v9, v171
	v_mov_b32_e32 v10, v171
	ds_write_b128 v2, v[32:35]
	v_mad_u64_u32 v[2:3], s[0:1], v68, s15, v[0:1]
	ds_write_b128 v2, v[36:39]
	v_mad_u64_u32 v[2:3], s[0:1], v70, s15, v[0:1]
	v_mov_b32_e32 v68, 0xf149f2ca
	v_mov_b32_e32 v11, v171
	v_mov_b32_e32 v12, v171
	v_mov_b32_e32 v13, v171
	v_mov_b32_e32 v14, v171
	v_mov_b32_e32 v15, v171
	v_mov_b32_e32 v16, 0
	v_mov_b32_e32 v17, v171
	ds_write_b128 v2, v[40:43]
	v_mad_u64_u32 v[2:3], s[0:1], v72, s15, v[0:1]
	ds_write_b128 v2, v[44:47]
	v_mad_u64_u32 v[2:3], s[0:1], v74, s15, v[0:1]
	v_mov_b32_e32 v18, v171
	v_mov_b32_e32 v19, v171
	v_mov_b32_e32 v20, v171
	v_mov_b32_e32 v21, v171
	v_mov_b32_e32 v22, v171
	v_mov_b32_e32 v23, v171
	v_mov_b32_e32 v24, v171
	v_mov_b32_e32 v25, v171
	v_mov_b32_e32 v26, v171
	ds_write_b128 v2, v[48:51]
	v_mad_u64_u32 v[2:3], s[0:1], v76, s15, v[0:1]
	ds_write_b128 v2, v[52:55]
	v_mad_u64_u32 v[2:3], s[0:1], v78, s15, v[0:1]
	v_mad_u64_u32 v[0:1], s[0:1], v80, s15, v[0:1]
	v_and_b32_e32 v1, 64, v237
	ds_write_b128 v2, v[56:59]
	ds_write_b128 v0, v[60:63]
	v_xor_b32_e32 v0, 32, v237
	v_add_u32_e32 v1, 64, v1
	v_cmp_lt_i32_e32 vcc, v0, v1
	s_mov_b32 s15, 0
	s_mov_b64 s[0:1], -1
	v_cndmask_b32_e32 v0, v237, v0, vcc
	v_lshlrev_b32_e32 v169, 2, v0
	v_mul_u32_u24_e32 v0, 0x210, v166
	v_add3_u32 v170, s16, v162, v0
	v_mov_b32_e32 v0, 0
	v_mov_b32_e32 v1, v171
	v_mov_b32_e32 v2, v171
	v_mov_b32_e32 v3, v171
	v_mov_b32_e32 v27, v171
	v_mov_b32_e32 v28, v171
	v_mov_b32_e32 v29, v171
	v_mov_b32_e32 v30, v171
	v_mov_b32_e32 v31, v171
	v_mov_b32_e32 v32, 0
	v_mov_b32_e32 v33, v171
	v_mov_b32_e32 v34, v171
	v_mov_b32_e32 v35, v171
	v_mov_b32_e32 v36, v171
	v_mov_b32_e32 v37, v171
	v_mov_b32_e32 v38, v171
	v_mov_b32_e32 v39, v171
	v_mov_b32_e32 v40, v171
	v_mov_b32_e32 v41, v171
	v_mov_b32_e32 v42, v171
	v_mov_b32_e32 v43, v171
	v_mov_b32_e32 v44, v171
	v_mov_b32_e32 v45, v171
	v_mov_b32_e32 v46, v171
	v_mov_b32_e32 v47, v171
	v_mov_b32_e32 v48, 0
	v_mov_b32_e32 v49, v171
	v_mov_b32_e32 v50, v171
	v_mov_b32_e32 v51, v171
	v_mov_b32_e32 v52, v171
	v_mov_b32_e32 v53, v171
	v_mov_b32_e32 v54, v171
	v_mov_b32_e32 v55, v171
	v_mov_b32_e32 v56, v171
	v_mov_b32_e32 v57, v171
	v_mov_b32_e32 v58, v171
	v_mov_b32_e32 v59, v171
	v_mov_b32_e32 v60, v171
	v_mov_b32_e32 v61, v171
	v_mov_b32_e32 v62, v171
	v_mov_b32_e32 v63, v171
	s_waitcnt lgkmcnt(0)
	s_barrier
	.p2align	6

; __global__ void __launch_bounds__(512, 2) mk_fwd(Args a) {
;     ...
;                 for (int it = vcu; it < total; it += G) {
;                     TID_LOCALS
;                     int lo = 0, hh = 511;
;                     while (lo < hh) { const int mid = (lo + hh) >> 1; if (pre[mid] > it) hh = mid; else lo = mid + 1; }
;                     const int p = lo, chunk = it - (p ? pre[p - 1] : 0), h = p >> 6, b = p & 63;
;                     const int pc = (int)CNT[l * 512 + p];
;                     const int e = chunk * 256 + 32 * wave + r32; const bool valid = e < pc;
;                     const unsigned ent = LIST[(size_t)p * SEQ + (valid ? e : 0)];
;                     u32x4 kr[8], vr[8];
;                     stage_kv_load(kr, vr, PROJ + (size_t)(256 * b) * INW + 1024 + 128 * h, INW, VT + (size_t)(h * 64 + b) * 128 * 256, tid);
.LBB0_51:
	s_ashr_i32 s7, s6, 31
	s_lshr_b32 s28, s6, 6
	s_and_b32 s18, s6, 63
	s_lshl_b64 s[16:17], s[6:7], 2
	v_mov_b32_e32 v2, s16
	v_add_u32_e32 v2, 0x23000, v2
	ds_read_b32 v12, v2
	s_mov_b32 s7, s75
	s_ashr_i32 s15, s15, 1
	s_lshl_b64 s[6:7], s[6:7], 16
	s_andn2_b32 s15, s15, 31
	s_waitcnt lgkmcnt(0)
	v_sub_u32_e32 v1, s14, v1
	s_add_u32 s16, s58, s6
	v_lshlrev_b32_e32 v1, 8, v1
	s_mul_i32 s18, s18, 0x280000
	s_addc_u32 s17, s59, s7
	v_add_u32_e32 v1, s15, v1
	s_add_u32 s15, s72, s18
	s_addc_u32 s19, s73, 0
	s_lshl_b32 s74, s28, 8
	v_lshlrev_b32_e32 v2, 4, v0
	s_add_u32 s18, s15, s74
	v_mov_b32_e32 v67, v129
	v_add_u32_e32 v3, 0x200, v0
	v_add_u32_e32 v4, 0x400, v0
	v_add_u32_e32 v6, 0x800, v0
	v_add_u32_e32 v7, 0xa00, v0
	v_and_b32_e32 v66, 0xf0, v2
	s_addc_u32 s19, s19, 0
	v_and_b32_e32 v163, 31, v0
	v_ashrrev_i32_e32 v88, 4, v0
	v_add_u32_e32 v8, 0xc00, v0
	v_add_u32_e32 v9, 0xe00, v0
	v_ashrrev_i32_e32 v90, 4, v3
	v_ashrrev_i32_e32 v92, 4, v4
	v_ashrrev_i32_e32 v96, 4, v6
	v_ashrrev_i32_e32 v98, 4, v7
	v_ashrrev_i32_e32 v78, 5, v6
	v_ashrrev_i32_e32 v80, 5, v7
	s_add_u32 s22, s96, s6
	v_lshl_add_u64 v[6:7], s[18:19], 0, v[66:67]
	s_movk_i32 s18, 0x2800
	v_ashrrev_i32_e32 v100, 4, v8
	v_ashrrev_i32_e32 v102, 4, v9
	v_and_b32_e32 v68, 0x1f0, v2
	v_ashrrev_i32_e32 v72, 5, v3
	v_ashrrev_i32_e32 v82, 5, v8
	v_ashrrev_i32_e32 v84, 5, v9
	v_or_b32_e32 v1, v1, v163
	s_addc_u32 s23, s97, s7
	v_mad_i64_i32 v[2:3], s[6:7], v88, s18, v[6:7]
	v_mad_i64_i32 v[8:9], s[6:7], v90, s18, v[6:7]
	v_mad_i64_i32 v[10:11], s[6:7], v92, s18, v[6:7]
	v_add_u32_e32 v5, 0x600, v0
	v_ashrrev_i32_e32 v70, 5, v0
	v_ashrrev_i32_e32 v74, 5, v4
	v_ashrrev_i32_e32 v76, 5, v5
	v_bfe_u32 v167, v0, 5, 1
	v_mov_b32_e32 v69, v129
	v_ashrrev_i32_e32 v71, 31, v70
	v_ashrrev_i32_e32 v73, 31, v72
	v_ashrrev_i32_e32 v75, 31, v74
	v_ashrrev_i32_e32 v77, 31, v76
	v_ashrrev_i32_e32 v79, 31, v78
	v_ashrrev_i32_e32 v81, 31, v80
	v_ashrrev_i32_e32 v83, 31, v82
	v_ashrrev_i32_e32 v85, 31, v84
	v_ashrrev_i32_e32 v94, 4, v5
	v_lshlrev_b64 v[34:35], 9, v[70:71]
	v_lshlrev_b64 v[36:37], 9, v[72:73]
	v_lshlrev_b64 v[38:39], 9, v[74:75]
	v_lshl_add_u64 v[62:63], s[22:23], 0, v[68:69]
	v_lshlrev_b64 v[46:47], 9, v[76:77]
	v_lshlrev_b64 v[50:51], 9, v[78:79]
	v_lshlrev_b64 v[54:55], 9, v[80:81]
	v_lshlrev_b64 v[58:59], 9, v[82:83]
	v_lshlrev_b64 v[64:65], 9, v[84:85]
	v_mov_b32_e32 v87, v129
	v_lshlrev_b32_e32 v86, 4, v167
	v_lshl_add_u64 v[34:35], v[62:63], 0, v[34:35]
	v_lshl_add_u64 v[40:41], v[62:63], 0, v[36:37]
	v_lshl_add_u64 v[42:43], v[62:63], 0, v[38:39]
	v_lshl_add_u64 v[46:47], v[62:63], 0, v[46:47]
	v_cmp_lt_i32_e64 s[6:7], v1, v12
	v_lshl_add_u64 v[50:51], v[62:63], 0, v[50:51]
	v_lshl_add_u64 v[54:55], v[62:63], 0, v[54:55]
	v_cndmask_b32_e64 v12, 0, v1, s[6:7]
	v_ashrrev_i32_e32 v13, 31, v12
	v_lshl_add_u64 v[12:13], v[12:13], 2, s[16:17]
	global_load_dword v168, v[12:13], off
	v_mov_b64_e32 v[0:1], s[72:73]
	v_mad_i64_i32 v[14:15], s[16:17], v94, s18, v[6:7]
	v_mad_i64_i32 v[18:19], s[16:17], v96, s18, v[6:7]
	v_mad_i64_i32 v[22:23], s[16:17], v98, s18, v[6:7]
	v_mad_i64_i32 v[26:27], s[16:17], v100, s18, v[6:7]
	v_mad_i64_i32 v[30:31], s[16:17], v102, s18, v[6:7]
	v_lshl_add_u64 v[58:59], v[62:63], 0, v[58:59]
	v_lshl_add_u64 v[62:63], v[62:63], 0, v[64:65]
	global_load_dwordx4 v[2:5], v[2:3], off offset:2048
	s_nop 0
	global_load_dwordx4 v[6:9], v[8:9], off offset:2048
	s_nop 0
	global_load_dwordx4 v[10:13], v[10:11], off offset:2048
	s_nop 0
	global_load_dwordx4 v[14:17], v[14:15], off offset:2048
	s_nop 0
	global_load_dwordx4 v[18:21], v[18:19], off offset:2048
	s_nop 0
	global_load_dwordx4 v[22:25], v[22:23], off offset:2048
	s_nop 0
	global_load_dwordx4 v[26:29], v[26:27], off offset:2048
	s_nop 0
	global_load_dwordx4 v[30:33], v[30:31], off offset:2048
	s_nop 0
	global_load_dwordx4 v[34:37], v[34:35], off
	s_nop 0
	global_load_dwordx4 v[38:41], v[40:41], off
	s_nop 0
	global_load_dwordx4 v[42:45], v[42:43], off
	v_readlane_b32 s19, v254, 28
	global_load_dwordx4 v[46:49], v[46:47], off
	v_add_u32_e32 v66, 0, v66
	global_load_dwordx4 v[50:53], v[50:51], off
	v_add_u32_e32 v68, s19, v68
	global_load_dwordx4 v[54:57], v[54:55], off
	s_movk_i32 s20, 0x210
	global_load_dwordx4 v[58:61], v[58:59], off
	v_mad_u64_u32 v[88:89], s[16:17], v88, s86, v[66:67]
	global_load_dwordx4 v[62:65], v[62:63], off
	v_mad_u64_u32 v[90:91], s[16:17], v90, s86, v[66:67]
	v_mad_u64_u32 v[92:93], s[16:17], v92, s86, v[66:67]
	v_mad_u64_u32 v[94:95], s[16:17], v94, s86, v[66:67]
	v_mad_u64_u32 v[96:97], s[16:17], v96, s86, v[66:67]
	v_mad_u64_u32 v[98:99], s[16:17], v98, s86, v[66:67]
	v_mad_u64_u32 v[100:101], s[16:17], v100, s86, v[66:67]
	v_mad_u64_u32 v[66:67], s[16:17], v102, s86, v[66:67]
	v_mad_u64_u32 v[70:71], s[16:17], v70, s20, v[68:69]
	v_mad_u64_u32 v[72:73], s[16:17], v72, s20, v[68:69]
	v_mad_u64_u32 v[74:75], s[16:17], v74, s20, v[68:69]
	v_lshlrev_b32_e32 v164, 3, v167
	s_mov_b32 s15, 0
	v_add_u32_e32 v169, 0, v86
	s_mov_b64 s[60:61], -1
	v_mov_b32_e32 v162, 0xf149f2ca
	s_waitcnt vmcnt(16)
; __global__ void __launch_bounds__(512, 2) mk_fwd(Args a) {
;     ...
;                     const int tok = (int)(ent >> 2), slot = (int)(ent & 3u);
;                     const bf16_t* qrow = PROJ + (size_t)tok * INW + 128 * h + 8 * hi;
;                     bf16x8 qf[8];
; #pragma unroll
;                     for (int d0 = 0; d0 < 8; ++d0) qf[d0] = *(const bf16x8*)(qrow + 16 * d0);
;                     stage_kv_store(lds, kr, vr, tid);
;                     __syncthreads();
;                     f32x16 O[4]; float m2, ll;
;                     attn_tile<false>(lds + LDS_KS, lds + LDS_VT, qf, 0, r32, hi, O, m2, ll);
	v_lshrrev_b32_e32 v128, 2, v168
	v_mad_u64_u32 v[0:1], s[16:17], v128, s18, v[0:1]
	v_lshl_add_u64 v[0:1], v[0:1], 0, s[74:75]
	v_lshl_add_u64 v[0:1], v[0:1], 0, v[86:87]
	global_load_dwordx4 v[130:133], v[0:1], off
	global_load_dwordx4 v[134:137], v[0:1], off offset:32
	global_load_dwordx4 v[138:141], v[0:1], off offset:64
	global_load_dwordx4 v[142:145], v[0:1], off offset:96
	global_load_dwordx4 v[146:149], v[0:1], off offset:128
	global_load_dwordx4 v[150:153], v[0:1], off offset:160
	global_load_dwordx4 v[154:157], v[0:1], off offset:192
	global_load_dwordx4 v[158:161], v[0:1], off offset:224
	v_mad_u64_u32 v[0:1], s[16:17], v76, s20, v[68:69]
	s_waitcnt vmcnt(8) lgkmcnt(0)
	ds_write_b128 v88, v[2:5]
	ds_write_b128 v90, v[6:9]
	ds_write_b128 v92, v[10:13]
	ds_write_b128 v94, v[14:17]
	ds_write_b128 v96, v[18:21]
	ds_write_b128 v98, v[22:25]
	ds_write_b128 v100, v[26:29]
	ds_write_b128 v66, v[30:33]
	ds_write_b128 v70, v[34:37]
	ds_write_b128 v72, v[38:41]
	ds_write_b128 v74, v[42:45]
	v_mov_b32_e32 v32, 0
	ds_write_b128 v0, v[46:49]
	v_mad_u64_u32 v[0:1], s[16:17], v78, s20, v[68:69]
	ds_write_b128 v0, v[50:53]
	v_mad_u64_u32 v[0:1], s[16:17], v80, s20, v[68:69]
	ds_write_b128 v0, v[54:57]
	v_mad_u64_u32 v[0:1], s[16:17], v82, s20, v[68:69]
	ds_write_b128 v0, v[58:61]
	v_mad_u64_u32 v[0:1], s[16:17], v84, s20, v[68:69]
	ds_write_b128 v0, v[62:65]
	v_mul_u32_u24_e32 v0, 0x210, v163
	v_add3_u32 v170, s19, v164, v0
	v_mov_b32_e32 v48, 0
	v_mov_b32_e32 v49, v171
	v_mov_b32_e32 v50, v171
	v_mov_b32_e32 v51, v171
	v_mov_b32_e32 v52, v171
	v_mov_b32_e32 v53, v171
	v_mov_b32_e32 v54, v171
	v_mov_b32_e32 v55, v171
	v_mov_b32_e32 v56, v171
	v_mov_b32_e32 v57, v171
	v_mov_b32_e32 v58, v171
	v_mov_b32_e32 v59, v171
	v_mov_b32_e32 v60, v171
	v_mov_b32_e32 v61, v171
	v_mov_b32_e32 v62, v171
	v_mov_b32_e32 v63, v171
	v_mov_b32_e32 v33, v171
	v_mov_b32_e32 v34, v171
	v_mov_b32_e32 v35, v171
	v_mov_b32_e32 v36, v171
	v_mov_b32_e32 v37, v171
	v_mov_b32_e32 v38, v171
	v_mov_b32_e32 v39, v171
	v_mov_b32_e32 v40, v171
	v_mov_b32_e32 v41, v171
	v_mov_b32_e32 v42, v171
	v_mov_b32_e32 v43, v171
	v_mov_b32_e32 v44, v171
	v_mov_b32_e32 v45, v171
	v_mov_b32_e32 v46, v171
	v_mov_b32_e32 v47, v171
	v_mov_b32_e32 v16, 0
	v_mov_b32_e32 v17, v171
	v_mov_b32_e32 v18, v171
	v_mov_b32_e32 v19, v171
	v_mov_b32_e32 v20, v171
	v_mov_b32_e32 v21, v171
	v_mov_b32_e32 v22, v171
	v_mov_b32_e32 v23, v171
	v_mov_b32_e32 v24, v171
	v_mov_b32_e32 v25, v171
	v_mov_b32_e32 v26, v171
	v_mov_b32_e32 v27, v171
	v_mov_b32_e32 v28, v171
	v_mov_b32_e32 v29, v171
	v_mov_b32_e32 v30, v171
	v_mov_b32_e32 v31, v171
	v_mov_b32_e32 v0, 0
	v_mov_b32_e32 v1, v171
	v_mov_b32_e32 v2, v171
	v_mov_b32_e32 v3, v171
	v_mov_b32_e32 v4, v171
	v_mov_b32_e32 v5, v171
	v_mov_b32_e32 v6, v171
	v_mov_b32_e32 v7, v171
	v_mov_b32_e32 v8, v171
	v_mov_b32_e32 v9, v171
	v_mov_b32_e32 v10, v171
	v_mov_b32_e32 v11, v171
	v_mov_b32_e32 v12, v171
	v_mov_b32_e32 v13, v171
	v_mov_b32_e32 v14, v171
	v_mov_b32_e32 v15, v171
	s_waitcnt lgkmcnt(0)
	s_barrier
	s_cmp_eq_u64 s[6:7], 0
	s_cbranch_scc1 .LBB0_46
	.p2align	6

; __global__ void __launch_bounds__(512, 2) mk_fwd(Args a) {
;     ...
;                         const int hm = sl - 12;
;                         { const int m = tid >> 1, hf = tid & 1;
;                           const f32x4* kr = (const f32x4*)(MKV + (size_t)(256 * l + m) * 2048 + 1024 * l + 128 * hm + 64 * hf);
;                           const f32x4* gk = (const f32x4*)((const float*)a.in[14] + l * HD + 64 * hf);
;                           f32x4 v[16]; float ss = 0.f;
; #pragma unroll
;                           for (int i = 0; i < 16; ++i) { v[i] = kr[i]; ss += (v[i][0] * v[i][0] + v[i][1] * v[i][1]) + (v[i][2] * v[i][2] + v[i][3] * v[i][3]); }
;                           ss += __shfl_xor(ss, 1);
.LBB0_397:
	s_ashr_i32 s6, s21, 6
	s_and_b32 s22, s21, 63
	s_bfe_u32 s0, s21, 0x20006
	s_and_b32 s1, s6, -4
	s_or_b32 s23, s0, s1
	s_lshl_b32 s24, s22, 8
	s_cmp_gt_i32 s23, 7
	s_mov_b64 s[0:1], -1
	s_cbranch_scc0 .LBB0_406
	s_cmp_gt_u32 s6, 11
	s_cbranch_scc0 .LBB0_402
	v_mov_b32_e32 v75, v232
	s_lshl_b32 s1, s23, 7
	v_ashrrev_i32_e32 v64, 1, v75
	v_add_u32_e32 v0, s20, v64
	v_ashrrev_i32_e32 v1, 31, v0
	v_lshlrev_b64 v[0:1], 13, v[0:1]
	v_and_b32_e32 v77, 1, v75
	v_lshl_add_u64 v[0:1], s[18:19], 0, v[0:1]
	s_add_i32 s74, s1, 0xfffffa00
	v_lshl_add_u64 v[0:1], s[74:75], 2, v[0:1]
	v_lshlrev_b32_e32 v128, 8, v77
	v_lshl_add_u64 v[72:73], v[0:1], 0, v[128:129]
	flat_load_dwordx4 v[44:47], v[72:73]
	flat_load_dwordx4 v[56:59], v[72:73] offset:16
	flat_load_dwordx4 v[52:55], v[72:73] offset:32
	flat_load_dwordx4 v[60:63], v[72:73] offset:48
	flat_load_dwordx4 v[24:27], v[72:73] offset:64
	flat_load_dwordx4 v[28:31], v[72:73] offset:80
	flat_load_dwordx4 v[36:39], v[72:73] offset:96
	flat_load_dwordx4 v[48:51], v[72:73] offset:112
	flat_load_dwordx4 v[16:19], v[72:73] offset:128
	flat_load_dwordx4 v[20:23], v[72:73] offset:144
	flat_load_dwordx4 v[32:35], v[72:73] offset:160
	v_mul_lo_u32 v64, v64, s86
	v_readfirstlane_b32 s0, v75
	v_readlane_b32 s2, v254, 28
	v_and_b32_e32 v165, 31, v75
	v_mov_b32_e32 v166, 0
	s_mov_b32 s14, s25
	s_mov_b32 s25, 0
	s_waitcnt vmcnt(0) lgkmcnt(0)
	v_pk_mul_f32 v[0:1], v[46:47], v[46:47]
	v_pk_mul_f32 v[2:3], v[44:45], v[44:45]
	s_nop 0
	v_pk_mov_b32 v[4:5], v[2:3], v[0:1] op_sel:[1,0]
	v_mov_b32_e32 v3, v1
	v_pk_add_f32 v[0:1], v[4:5], v[2:3]
	v_pk_mul_f32 v[2:3], v[58:59], v[58:59]
	v_pk_mul_f32 v[4:5], v[56:57], v[56:57]
	v_pk_add_f32 v[0:1], v[0:1], v[0:1] op_sel:[0,1] op_sel_hi:[1,0]
	v_pk_mov_b32 v[6:7], v[4:5], v[2:3] op_sel:[1,0]
	v_mov_b32_e32 v5, v3
	v_pk_add_f32 v[2:3], v[6:7], v[4:5]
	v_mul_f32_e32 v4, v60, v60
	v_mul_f32_e32 v5, v61, v61
	v_pk_add_f32 v[2:3], v[2:3], v[2:3] op_sel:[0,1] op_sel_hi:[1,0]
	v_mov_b32_e32 v1, v4
	v_mov_b32_e32 v3, v5
	v_pk_add_f32 v[0:1], v[0:1], v[2:3]
	v_mul_f32_e32 v2, v53, v53
	v_mul_f32_e32 v4, v55, v55
	v_mul_f32_e32 v6, v62, v62
	v_mul_f32_e32 v7, v63, v63
	v_pk_fma_f32 v[2:3], v[52:53], v[52:53], v[2:3] op_sel_hi:[1,1,0]
	v_pk_fma_f32 v[4:5], v[54:55], v[54:55], v[4:5] op_sel_hi:[1,1,0]
	v_mov_b32_e32 v3, v6
	v_mov_b32_e32 v5, v7
	v_pk_add_f32 v[2:3], v[2:3], v[4:5]
	v_pk_mul_f32 v[4:5], v[24:25], v[24:25]
	v_pk_add_f32 v[0:1], v[0:1], v[2:3]
	v_pk_mul_f32 v[2:3], v[26:27], v[26:27]
	v_pk_add_f32 v[0:1], v[0:1], v[0:1] op_sel:[0,1] op_sel_hi:[1,0]
	v_pk_mov_b32 v[6:7], v[4:5], v[2:3] op_sel:[1,0]
	v_mov_b32_e32 v5, v3
	v_pk_add_f32 v[2:3], v[6:7], v[4:5]
	v_mul_f32_e32 v4, v36, v36
	v_mul_f32_e32 v5, v37, v37
	v_pk_add_f32 v[2:3], v[2:3], v[2:3] op_sel:[0,1] op_sel_hi:[1,0]
	v_mov_b32_e32 v1, v4
	v_mov_b32_e32 v3, v5
	v_pk_add_f32 v[0:1], v[0:1], v[2:3]
	v_mul_f32_e32 v2, v29, v29
	v_mul_f32_e32 v4, v31, v31
	v_mul_f32_e32 v6, v38, v38
	v_mul_f32_e32 v7, v39, v39
	v_pk_fma_f32 v[2:3], v[28:29], v[28:29], v[2:3] op_sel_hi:[1,1,0]
	v_pk_fma_f32 v[4:5], v[30:31], v[30:31], v[4:5] op_sel_hi:[1,1,0]
	v_mov_b32_e32 v3, v6
	v_mov_b32_e32 v5, v7
	v_pk_add_f32 v[2:3], v[2:3], v[4:5]
	v_pk_mul_f32 v[4:5], v[48:49], v[48:49]
	v_pk_add_f32 v[0:1], v[0:1], v[2:3]
	v_pk_mul_f32 v[2:3], v[50:51], v[50:51]
	v_pk_add_f32 v[0:1], v[0:1], v[0:1] op_sel:[0,1] op_sel_hi:[1,0]
	v_pk_mov_b32 v[6:7], v[4:5], v[2:3] op_sel:[1,0]
	v_mov_b32_e32 v5, v3
	v_pk_add_f32 v[2:3], v[6:7], v[4:5]
	v_mul_f32_e32 v4, v20, v20
	v_mul_f32_e32 v5, v21, v21
	v_pk_add_f32 v[2:3], v[2:3], v[2:3] op_sel:[0,1] op_sel_hi:[1,0]
	v_mov_b32_e32 v1, v4
	v_mov_b32_e32 v3, v5
	v_pk_add_f32 v[0:1], v[0:1], v[2:3]
	v_mul_f32_e32 v2, v17, v17
	v_mul_f32_e32 v4, v19, v19
	v_mul_f32_e32 v6, v22, v22
	v_mul_f32_e32 v7, v23, v23
	v_pk_fma_f32 v[2:3], v[16:17], v[16:17], v[2:3] op_sel_hi:[1,1,0]
	v_pk_fma_f32 v[4:5], v[18:19], v[18:19], v[4:5] op_sel_hi:[1,1,0]
	v_mov_b32_e32 v3, v6
	v_mov_b32_e32 v5, v7
	v_pk_add_f32 v[2:3], v[2:3], v[4:5]
	s_nop 0
	v_pk_add_f32 v[4:5], v[0:1], v[2:3]
	v_pk_mul_f32 v[0:1], v[34:35], v[34:35]
	v_pk_mul_f32 v[2:3], v[32:33], v[32:33]
	v_pk_add_f32 v[4:5], v[4:5], v[4:5] op_sel:[0,1] op_sel_hi:[1,0]
	v_pk_mov_b32 v[6:7], v[2:3], v[0:1] op_sel:[1,0]
	v_mov_b32_e32 v3, v1
	v_pk_add_f32 v[6:7], v[6:7], v[2:3]
	flat_load_dwordx4 v[40:43], v[72:73] offset:176
	flat_load_dwordx4 v[0:3], v[72:73] offset:192
	v_pk_add_f32 v[6:7], v[6:7], v[6:7] op_sel:[0,1] op_sel_hi:[1,0]
	s_waitcnt vmcnt(0) lgkmcnt(0)
	v_mul_f32_e32 v8, v0, v0
	v_mul_f32_e32 v9, v1, v1
	v_mov_b32_e32 v5, v8
	v_mov_b32_e32 v7, v9
	v_pk_add_f32 v[4:5], v[4:5], v[6:7]
	v_mul_f32_e32 v6, v41, v41
	v_mul_f32_e32 v8, v43, v43
	v_mul_f32_e32 v10, v2, v2
	v_mul_f32_e32 v11, v3, v3
	v_pk_fma_f32 v[6:7], v[40:41], v[40:41], v[6:7] op_sel_hi:[1,1,0]
	v_pk_fma_f32 v[8:9], v[42:43], v[42:43], v[8:9] op_sel_hi:[1,1,0]
	v_mov_b32_e32 v7, v10
	v_mov_b32_e32 v9, v11
	v_pk_add_f32 v[6:7], v[6:7], v[8:9]
	s_nop 0
	v_pk_add_f32 v[66:67], v[4:5], v[6:7]
	flat_load_dwordx4 v[4:7], v[72:73] offset:208
	v_pk_add_f32 v[66:67], v[66:67], v[66:67] op_sel:[0,1] op_sel_hi:[1,0]
	s_waitcnt vmcnt(0) lgkmcnt(0)
	v_pk_mul_f32 v[8:9], v[6:7], v[6:7]
	v_pk_mul_f32 v[10:11], v[4:5], v[4:5]
	s_nop 0
	v_pk_mov_b32 v[12:13], v[10:11], v[8:9] op_sel:[1,0]
	v_mov_b32_e32 v11, v9
	v_pk_add_f32 v[68:69], v[12:13], v[10:11]
	flat_load_dwordx4 v[12:15], v[72:73] offset:224
	flat_load_dwordx4 v[8:11], v[72:73] offset:240
	v_pk_add_f32 v[68:69], v[68:69], v[68:69] op_sel:[0,1] op_sel_hi:[1,0]
	s_waitcnt vmcnt(0) lgkmcnt(0)
; #define LAS __attribute__((address_space(3)))
; __device__ __forceinline__ unsigned cvtpk(float lo, float hi) { f32x2 v = {lo, hi}; bf16x2_t b = __builtin_convertvector(v, bf16x2_t); return __builtin_bit_cast(unsigned, b); }
; __global__ void __launch_bounds__(512, 2) mk_fwd(Args a) {
;     ...
;                           ss += __shfl_xor(ss, 1);
;                           const float rstd = 1.0f / sqrtf(ss * (1.0f / 128.0f) + 1e-6f);
; #pragma unroll
;                           for (int i = 0; i < 8; ++i) { const f32x4 g0 = gk[2 * i], g1 = gk[2 * i + 1]; const f32x4 p0 = v[2 * i] * rstd * g0, p1 = v[2 * i + 1] * rstd * g1;
;                               u32x4 o; o.x = cvtpk(p0[0], p0[1]); o.y = cvtpk(p0[2], p0[3]); o.z = cvtpk(p1[0], p1[1]); o.w = cvtpk(p1[2], p1[3]);
;                               *(LAS u32x4*)(lds + LDS_KS + m * KS_STRIDE + 128 * hf + 16 * i) = o; }
	v_mul_f32_e32 v65, v8, v8
	v_mul_f32_e32 v70, v9, v9
	v_mov_b32_e32 v67, v65
	v_mov_b32_e32 v69, v70
	v_pk_add_f32 v[66:67], v[66:67], v[68:69]
	v_mul_f32_e32 v68, v13, v13
	v_mul_f32_e32 v71, v10, v10
	v_pk_fma_f32 v[68:69], v[12:13], v[12:13], v[68:69] op_sel_hi:[1,1,0]
	v_mul_f32_e32 v70, v15, v15
	v_mul_f32_e32 v74, v11, v11
	v_mov_b32_e32 v69, v71
	v_pk_fma_f32 v[70:71], v[14:15], v[14:15], v[70:71] op_sel_hi:[1,1,0]
	s_nop 0
	v_mov_b32_e32 v71, v74
	v_pk_add_f32 v[68:69], v[68:69], v[70:71]
	s_nop 0
	v_pk_add_f32 v[66:67], v[66:67], v[68:69]
	s_nop 0
	v_add_f32_e32 v65, v66, v67
	v_and_b32_e32 v67, 64, v237
	v_xor_b32_e32 v66, 1, v237
	v_add_u32_e32 v76, 64, v67
	v_cmp_lt_i32_e32 vcc, v66, v76
	s_nop 1
	v_cndmask_b32_e32 v66, v237, v66, vcc
	v_lshlrev_b32_e32 v66, 2, v66
	ds_bpermute_b32 v66, v66, v65
	s_waitcnt lgkmcnt(0)
	v_add_f32_e32 v65, v65, v66
	v_fmamk_f32 v65, v65, 0x3c000000, v234
	v_cmp_gt_f32_e32 vcc, s33, v65
	v_mul_f32_e32 v66, 0x4f800000, v65
	s_nop 0
	v_cndmask_b32_e32 v65, v65, v66, vcc
	v_sqrt_f32_e32 v66, v65
	s_nop 0
	v_add_u32_e32 v67, -1, v66
	v_fma_f32 v68, -v67, v66, v65
	v_cmp_ge_f32_e64 s[6:7], 0, v68
	v_add_u32_e32 v68, 1, v66
	s_nop 0
	v_cndmask_b32_e64 v67, v66, v67, s[6:7]
	v_fma_f32 v66, -v68, v66, v65
	v_cmp_lt_f32_e64 s[6:7], 0, v66
	s_nop 1
	v_cndmask_b32_e64 v66, v67, v68, s[6:7]
	v_mul_f32_e32 v67, 0x37800000, v66
	v_cndmask_b32_e32 v66, v66, v67, vcc
	v_cmp_class_f32_e32 vcc, v65, v235
	s_nop 1
	v_cndmask_b32_e32 v65, v66, v65, vcc
	v_div_scale_f32 v66, s[6:7], v65, v65, 1.0
	v_rcp_f32_e32 v67, v66
	s_nop 0
	v_fma_f32 v68, -v66, v67, 1.0
	v_fmac_f32_e32 v67, v68, v67
	v_div_scale_f32 v68, vcc, 1.0, v65, 1.0
	v_mul_f32_e32 v69, v68, v67
	v_fma_f32 v70, -v66, v69, v68
	v_fmac_f32_e32 v69, v70, v67
	v_fma_f32 v66, -v66, v69, v68
	v_div_fmas_f32 v66, v66, v67, v69
	v_div_fixup_f32 v74, v66, v65, 1.0
	v_lshlrev_b32_e32 v65, 7, v77
	v_add3_u32 v78, 0, v64, v65
	global_load_dwordx4 v[64:67], v128, s[30:31] offset:48
	global_load_dwordx4 v[68:71], v128, s[30:31] offset:32
	global_load_dwordx4 v[80:83], v128, s[30:31] offset:16
	global_load_dwordx4 v[84:87], v128, s[30:31]
	v_pk_mul_f32 v[44:45], v[74:75], v[44:45] op_sel_hi:[0,1]
	v_pk_mul_f32 v[46:47], v[74:75], v[46:47] op_sel_hi:[0,1]
	v_pk_mul_f32 v[56:57], v[74:75], v[56:57] op_sel_hi:[0,1]
	v_pk_mul_f32 v[58:59], v[74:75], v[58:59] op_sel_hi:[0,1]
	v_pk_mul_f32 v[24:25], v[74:75], v[24:25] op_sel_hi:[0,1]
	v_pk_mul_f32 v[26:27], v[74:75], v[26:27] op_sel_hi:[0,1]
	v_pk_mul_f32 v[28:29], v[74:75], v[28:29] op_sel_hi:[0,1]
	v_pk_mul_f32 v[30:31], v[74:75], v[30:31] op_sel_hi:[0,1]
	v_pk_mul_f32 v[16:17], v[74:75], v[16:17] op_sel_hi:[0,1]
	v_pk_mul_f32 v[18:19], v[74:75], v[18:19] op_sel_hi:[0,1]
	v_pk_mul_f32 v[20:21], v[74:75], v[20:21] op_sel_hi:[0,1]
	v_pk_mul_f32 v[22:23], v[74:75], v[22:23] op_sel_hi:[0,1]
	v_pk_mul_f32 v[0:1], v[74:75], v[0:1] op_sel_hi:[0,1]
	v_pk_mul_f32 v[2:3], v[74:75], v[2:3] op_sel_hi:[0,1]
	v_pk_mul_f32 v[4:5], v[74:75], v[4:5] op_sel_hi:[0,1]
	v_pk_mul_f32 v[6:7], v[74:75], v[6:7] op_sel_hi:[0,1]
	s_waitcnt vmcnt(1)
	v_pk_mul_f32 v[58:59], v[82:83], v[58:59]
	s_waitcnt vmcnt(0)
	v_pk_mul_f32 v[46:47], v[86:87], v[46:47]
	v_pk_mul_f32 v[44:45], v[84:85], v[44:45]
	v_pk_mul_f32 v[56:57], v[80:81], v[56:57]
	v_cvt_pk_bf16_f32 v44, v44, v45
	v_cvt_pk_bf16_f32 v45, v46, v47
	v_cvt_pk_bf16_f32 v46, v56, v57
	v_cvt_pk_bf16_f32 v47, v58, v59
	ds_write_b128 v78, v[44:47]
	v_pk_mul_f32 v[44:45], v[74:75], v[52:53] op_sel_hi:[0,1]
	v_pk_mul_f32 v[46:47], v[74:75], v[54:55] op_sel_hi:[0,1]
	v_pk_mul_f32 v[52:53], v[74:75], v[60:61] op_sel_hi:[0,1]
	v_pk_mul_f32 v[54:55], v[74:75], v[62:63] op_sel_hi:[0,1]
	v_pk_mul_f32 v[46:47], v[70:71], v[46:47]
	v_pk_mul_f32 v[44:45], v[68:69], v[44:45]
	v_pk_mul_f32 v[54:55], v[66:67], v[54:55]
	v_pk_mul_f32 v[52:53], v[64:65], v[52:53]
	v_cvt_pk_bf16_f32 v44, v44, v45
	v_cvt_pk_bf16_f32 v45, v46, v47
	v_cvt_pk_bf16_f32 v46, v52, v53
	v_cvt_pk_bf16_f32 v47, v54, v55
	ds_write_b128 v78, v[44:47] offset:16
	global_load_dwordx4 v[44:47], v128, s[30:31] offset:112
	global_load_dwordx4 v[52:55], v128, s[30:31] offset:96
	global_load_dwordx4 v[56:59], v128, s[30:31] offset:80
	global_load_dwordx4 v[60:63], v128, s[30:31] offset:64
	s_waitcnt vmcnt(1)
	v_pk_mul_f32 v[30:31], v[58:59], v[30:31]
	s_waitcnt vmcnt(0)
	v_pk_mul_f32 v[26:27], v[62:63], v[26:27]
	v_pk_mul_f32 v[24:25], v[60:61], v[24:25]
	v_pk_mul_f32 v[28:29], v[56:57], v[28:29]
	v_cvt_pk_bf16_f32 v24, v24, v25
	v_cvt_pk_bf16_f32 v25, v26, v27
	v_cvt_pk_bf16_f32 v26, v28, v29
	v_cvt_pk_bf16_f32 v27, v30, v31
	ds_write_b128 v78, v[24:27] offset:32
	v_pk_mul_f32 v[24:25], v[74:75], v[36:37] op_sel_hi:[0,1]
	v_pk_mul_f32 v[26:27], v[74:75], v[38:39] op_sel_hi:[0,1]
	v_pk_mul_f32 v[28:29], v[74:75], v[48:49] op_sel_hi:[0,1]
	v_pk_mul_f32 v[30:31], v[74:75], v[50:51] op_sel_hi:[0,1]
	v_pk_mul_f32 v[26:27], v[54:55], v[26:27]
	v_pk_mul_f32 v[24:25], v[52:53], v[24:25]
	v_pk_mul_f32 v[30:31], v[46:47], v[30:31]
	v_pk_mul_f32 v[28:29], v[44:45], v[28:29]
	v_cvt_pk_bf16_f32 v24, v24, v25
	v_cvt_pk_bf16_f32 v25, v26, v27
	v_cvt_pk_bf16_f32 v26, v28, v29
	v_cvt_pk_bf16_f32 v27, v30, v31
	ds_write_b128 v78, v[24:27] offset:48
	global_load_dwordx4 v[24:27], v128, s[30:31] offset:176
	global_load_dwordx4 v[28:31], v128, s[30:31] offset:160
	global_load_dwordx4 v[36:39], v128, s[30:31] offset:144
	global_load_dwordx4 v[44:47], v128, s[30:31] offset:128
	s_waitcnt vmcnt(1)
	v_pk_mul_f32 v[22:23], v[38:39], v[22:23]
	s_waitcnt vmcnt(0)
; #define LAS __attribute__((address_space(3)))
; __device__ __forceinline__ unsigned cvtpk(float lo, float hi) { f32x2 v = {lo, hi}; bf16x2_t b = __builtin_convertvector(v, bf16x2_t); return __builtin_bit_cast(unsigned, b); }
; __global__ void __launch_bounds__(512, 2) mk_fwd(Args a) {
;     ...
;                           for (int i = 0; i < 8; ++i) { const f32x4 g0 = gk[2 * i], g1 = gk[2 * i + 1]; const f32x4 p0 = v[2 * i] * rstd * g0, p1 = v[2 * i + 1] * rstd * g1;
;                               u32x4 o; o.x = cvtpk(p0[0], p0[1]); o.y = cvtpk(p0[2], p0[3]); o.z = cvtpk(p1[0], p1[1]); o.w = cvtpk(p1[2], p1[3]);
;                               *(LAS u32x4*)(lds + LDS_KS + m * KS_STRIDE + 128 * hf + 16 * i) = o; }
;                           const f32x4* vr = kr + 128;
; #pragma unroll
;                           for (int i = 0; i < 16; ++i) { const f32x4 vv = vr[i];
; #pragma unroll
;                               for (int e = 0; e < 4; ++e) *(LAS bf16_t*)(lds + LDS_VT + (64 * hf + 4 * i + e) * VT_STRIDE + 2 * m) = (bf16_t)(cvtpk(vv[e], 0.f) & 0xffffu); }
	v_pk_mul_f32 v[18:19], v[46:47], v[18:19]
	v_pk_mul_f32 v[16:17], v[44:45], v[16:17]
	v_pk_mul_f32 v[20:21], v[36:37], v[20:21]
	v_cvt_pk_bf16_f32 v16, v16, v17
	v_cvt_pk_bf16_f32 v17, v18, v19
	v_cvt_pk_bf16_f32 v18, v20, v21
	v_cvt_pk_bf16_f32 v19, v22, v23
	ds_write_b128 v78, v[16:19] offset:64
	v_pk_mul_f32 v[16:17], v[74:75], v[32:33] op_sel_hi:[0,1]
	v_pk_mul_f32 v[18:19], v[74:75], v[34:35] op_sel_hi:[0,1]
	v_pk_mul_f32 v[20:21], v[74:75], v[40:41] op_sel_hi:[0,1]
	v_pk_mul_f32 v[22:23], v[74:75], v[42:43] op_sel_hi:[0,1]
	v_pk_mul_f32 v[18:19], v[30:31], v[18:19]
	v_pk_mul_f32 v[16:17], v[28:29], v[16:17]
	v_pk_mul_f32 v[22:23], v[26:27], v[22:23]
	v_pk_mul_f32 v[20:21], v[24:25], v[20:21]
	v_cvt_pk_bf16_f32 v16, v16, v17
	v_cvt_pk_bf16_f32 v17, v18, v19
	v_cvt_pk_bf16_f32 v18, v20, v21
	v_cvt_pk_bf16_f32 v19, v22, v23
	ds_write_b128 v78, v[16:19] offset:80
	global_load_dwordx4 v[16:19], v128, s[30:31] offset:240
	global_load_dwordx4 v[20:23], v128, s[30:31] offset:224
	global_load_dwordx4 v[24:27], v128, s[30:31] offset:208
	global_load_dwordx4 v[28:31], v128, s[30:31] offset:192
	s_waitcnt vmcnt(1)
	v_pk_mul_f32 v[6:7], v[26:27], v[6:7]
	s_waitcnt vmcnt(0)
	v_pk_mul_f32 v[2:3], v[30:31], v[2:3]
	v_pk_mul_f32 v[0:1], v[28:29], v[0:1]
	v_pk_mul_f32 v[4:5], v[24:25], v[4:5]
	v_cvt_pk_bf16_f32 v0, v0, v1
	v_cvt_pk_bf16_f32 v1, v2, v3
	v_cvt_pk_bf16_f32 v2, v4, v5
	v_cvt_pk_bf16_f32 v3, v6, v7
	ds_write_b128 v78, v[0:3] offset:96
	v_pk_mul_f32 v[0:1], v[74:75], v[12:13] op_sel_hi:[0,1]
	v_pk_mul_f32 v[2:3], v[74:75], v[14:15] op_sel_hi:[0,1]
	v_pk_mul_f32 v[4:5], v[74:75], v[8:9] op_sel_hi:[0,1]
	v_pk_mul_f32 v[6:7], v[74:75], v[10:11] op_sel_hi:[0,1]
	v_pk_mul_f32 v[2:3], v[22:23], v[2:3]
	v_pk_mul_f32 v[0:1], v[20:21], v[0:1]
	v_pk_mul_f32 v[6:7], v[18:19], v[6:7]
	v_pk_mul_f32 v[4:5], v[16:17], v[4:5]
	v_cvt_pk_bf16_f32 v0, v0, v1
	v_cvt_pk_bf16_f32 v1, v2, v3
	v_cvt_pk_bf16_f32 v2, v4, v5
	v_cvt_pk_bf16_f32 v3, v6, v7
	ds_write_b128 v78, v[0:3] offset:112
	v_and_b32_e32 v4, -2, v75
	v_mul_u32_u24_e32 v5, 0x8400, v77
	v_add3_u32 v4, s2, v4, v5
	global_load_dwordx4 v[0:3], v[72:73], off offset:2048
	global_load_dwordx4 v[8:11], v[72:73], off offset:2064
	global_load_dwordx4 v[12:15], v[72:73], off offset:2080
	global_load_dwordx4 v[16:19], v[72:73], off offset:2096
	global_load_dwordx4 v[20:23], v[72:73], off offset:2112
	global_load_dwordx4 v[24:27], v[72:73], off offset:2128
	global_load_dwordx4 v[28:31], v[72:73], off offset:2144
	global_load_dwordx4 v[32:35], v[72:73], off offset:2160
	global_load_dwordx4 v[36:39], v[72:73], off offset:2176
	global_load_dwordx4 v[40:43], v[72:73], off offset:2192
	global_load_dwordx4 v[44:47], v[72:73], off offset:2208
	global_load_dwordx4 v[48:51], v[72:73], off offset:2224
	global_load_dwordx4 v[52:55], v[72:73], off offset:2240
	global_load_dwordx4 v[56:59], v[72:73], off offset:2256
	global_load_dwordx4 v[60:63], v[72:73], off offset:2272
	global_load_dwordx4 v[64:67], v[72:73], off offset:2288
	s_waitcnt vmcnt(0) lgkmcnt(0)
	v_cvt_pk_bf16_f32 v0, v0, s0
	ds_write_b16 v4, v0
	v_cvt_pk_bf16_f32 v1, v1, s0
	ds_write_b16 v4, v1 offset:528
	v_cvt_pk_bf16_f32 v2, v2, s0
	ds_write_b16 v4, v2 offset:1056
	v_cvt_pk_bf16_f32 v3, v3, s0
	ds_write_b16 v4, v3 offset:1584
	v_cvt_pk_bf16_f32 v8, v8, s0
	ds_write_b16 v4, v8 offset:2112
	v_cvt_pk_bf16_f32 v9, v9, s0
	ds_write_b16 v4, v9 offset:2640
	v_cvt_pk_bf16_f32 v10, v10, s0
	ds_write_b16 v4, v10 offset:3168
	v_cvt_pk_bf16_f32 v11, v11, s0
	ds_write_b16 v4, v11 offset:3696
	v_cvt_pk_bf16_f32 v12, v12, s0
	ds_write_b16 v4, v12 offset:4224
	v_cvt_pk_bf16_f32 v13, v13, s0
	ds_write_b16 v4, v13 offset:4752
	v_cvt_pk_bf16_f32 v14, v14, s0
	ds_write_b16 v4, v14 offset:5280
	v_cvt_pk_bf16_f32 v15, v15, s0
	ds_write_b16 v4, v15 offset:5808
	v_cvt_pk_bf16_f32 v16, v16, s0
	ds_write_b16 v4, v16 offset:6336
	v_cvt_pk_bf16_f32 v17, v17, s0
	ds_write_b16 v4, v17 offset:6864
	v_cvt_pk_bf16_f32 v18, v18, s0
	ds_write_b16 v4, v18 offset:7392
	v_cvt_pk_bf16_f32 v19, v19, s0
	ds_write_b16 v4, v19 offset:7920
	v_cvt_pk_bf16_f32 v20, v20, s0
	ds_write_b16 v4, v20 offset:8448
	v_cvt_pk_bf16_f32 v21, v21, s0
	ds_write_b16 v4, v21 offset:8976
	v_cvt_pk_bf16_f32 v22, v22, s0
	ds_write_b16 v4, v22 offset:9504
	v_cvt_pk_bf16_f32 v23, v23, s0
	ds_write_b16 v4, v23 offset:10032
	v_cvt_pk_bf16_f32 v24, v24, s0
	ds_write_b16 v4, v24 offset:10560
	v_cvt_pk_bf16_f32 v25, v25, s0
	ds_write_b16 v4, v25 offset:11088
	v_cvt_pk_bf16_f32 v26, v26, s0
	ds_write_b16 v4, v26 offset:11616
	v_cvt_pk_bf16_f32 v27, v27, s0
	ds_write_b16 v4, v27 offset:12144
	v_cvt_pk_bf16_f32 v28, v28, s0
	ds_write_b16 v4, v28 offset:12672
	v_cvt_pk_bf16_f32 v29, v29, s0
	ds_write_b16 v4, v29 offset:13200
	v_cvt_pk_bf16_f32 v30, v30, s0
	ds_write_b16 v4, v30 offset:13728
	v_cvt_pk_bf16_f32 v31, v31, s0
	ds_write_b16 v4, v31 offset:14256
	v_cvt_pk_bf16_f32 v32, v32, s0
	ds_write_b16 v4, v32 offset:14784
	v_cvt_pk_bf16_f32 v33, v33, s0
	ds_write_b16 v4, v33 offset:15312
	v_cvt_pk_bf16_f32 v34, v34, s0
	ds_write_b16 v4, v34 offset:15840
	v_cvt_pk_bf16_f32 v35, v35, s0
	ds_write_b16 v4, v35 offset:16368
	v_cvt_pk_bf16_f32 v36, v36, s0
	ds_write_b16 v4, v36 offset:16896
	v_cvt_pk_bf16_f32 v37, v37, s0
	ds_write_b16 v4, v37 offset:17424
	v_cvt_pk_bf16_f32 v38, v38, s0
	ds_write_b16 v4, v38 offset:17952
	v_cvt_pk_bf16_f32 v39, v39, s0
	ds_write_b16 v4, v39 offset:18480
	v_cvt_pk_bf16_f32 v40, v40, s0
	ds_write_b16 v4, v40 offset:19008
	v_cvt_pk_bf16_f32 v41, v41, s0
	ds_write_b16 v4, v41 offset:19536
	v_cvt_pk_bf16_f32 v42, v42, s0
	ds_write_b16 v4, v42 offset:20064
	v_cvt_pk_bf16_f32 v43, v43, s0
; #define LAS __attribute__((address_space(3)))
; __device__ __forceinline__ unsigned cvtpk(float lo, float hi) { f32x2 v = {lo, hi}; bf16x2_t b = __builtin_convertvector(v, bf16x2_t); return __builtin_bit_cast(unsigned, b); }
; __device__ __forceinline__ float bflo(unsigned w) { return __uint_as_float(w << 16); }
; __device__ __forceinline__ float bfhi(unsigned w) { return __uint_as_float(w & 0xffff0000u); }
; __global__ void __launch_bounds__(512, 2) mk_fwd(Args a) {
;     ...
;                               for (int e = 0; e < 4; ++e) *(LAS bf16_t*)(lds + LDS_VT + (64 * hf + 4 * i + e) * VT_STRIDE + 2 * m) = (bf16_t)(cvtpk(vv[e], 0.f) & 0xffffu); }
;                         }
;                         __syncthreads();
;                         const int tok = tok0 + 32 * wave + r32;
;                         const bf16_t* qrow = PROJ + (size_t)tok * INW + 4608 + 128 * hm + 8 * hi;
;                         const float* gq = (const float*)a.in[13] + l * HD + 8 * hi;
;                         u32x4 qr[8]; float ss = 0.f;
; #pragma unroll
;                         for (int d0 = 0; d0 < 8; ++d0) { qr[d0] = *(const u32x4*)(qrow + 16 * d0);
; #pragma unroll
;                             for (int e = 0; e < 4; ++e) { const float lo = bflo(qr[d0][e]), hh = bfhi(qr[d0][e]); ss += lo * lo + hh * hh; } }
	ds_write_b16 v4, v43 offset:20592
	v_cvt_pk_bf16_f32 v44, v44, s0
	ds_write_b16 v4, v44 offset:21120
	v_cvt_pk_bf16_f32 v45, v45, s0
	ds_write_b16 v4, v45 offset:21648
	v_cvt_pk_bf16_f32 v46, v46, s0
	ds_write_b16 v4, v46 offset:22176
	v_cvt_pk_bf16_f32 v47, v47, s0
	ds_write_b16 v4, v47 offset:22704
	v_cvt_pk_bf16_f32 v48, v48, s0
	ds_write_b16 v4, v48 offset:23232
	v_cvt_pk_bf16_f32 v49, v49, s0
	ds_write_b16 v4, v49 offset:23760
	v_cvt_pk_bf16_f32 v50, v50, s0
	ds_write_b16 v4, v50 offset:24288
	v_cvt_pk_bf16_f32 v51, v51, s0
	ds_write_b16 v4, v51 offset:24816
	v_cvt_pk_bf16_f32 v52, v52, s0
	ds_write_b16 v4, v52 offset:25344
	v_cvt_pk_bf16_f32 v53, v53, s0
	ds_write_b16 v4, v53 offset:25872
	v_cvt_pk_bf16_f32 v54, v54, s0
	ds_write_b16 v4, v54 offset:26400
	v_cvt_pk_bf16_f32 v55, v55, s0
	ds_write_b16 v4, v55 offset:26928
	v_cvt_pk_bf16_f32 v56, v56, s0
	ds_write_b16 v4, v56 offset:27456
	v_cvt_pk_bf16_f32 v57, v57, s0
	ds_write_b16 v4, v57 offset:27984
	v_cvt_pk_bf16_f32 v58, v58, s0
	ds_write_b16 v4, v58 offset:28512
	v_cvt_pk_bf16_f32 v59, v59, s0
	ds_write_b16 v4, v59 offset:29040
	v_cvt_pk_bf16_f32 v60, v60, s0
	ds_write_b16 v4, v60 offset:29568
	v_cvt_pk_bf16_f32 v61, v61, s0
	ds_write_b16 v4, v61 offset:30096
	v_cvt_pk_bf16_f32 v62, v62, s0
	ds_write_b16 v4, v62 offset:30624
	v_cvt_pk_bf16_f32 v63, v63, s0
	ds_write_b16 v4, v63 offset:31152
	v_cvt_pk_bf16_f32 v64, v64, s0
	ds_write_b16 v4, v64 offset:31680
	v_cvt_pk_bf16_f32 v65, v65, s0
	ds_write_b16 v4, v65 offset:32208
	v_cvt_pk_bf16_f32 v66, v66, s0
	ds_write_b16 v4, v66 offset:32736
	v_cvt_pk_bf16_f32 v67, v67, s0
	ds_write_b16 v4, v67 offset:33264
	s_ashr_i32 s0, s0, 1
	s_andn2_b32 s0, s0, 31
	s_add_i32 s0, s0, s24
	v_or_b32_e32 v162, s0, v165
	v_mov_b64_e32 v[0:1], s[72:73]
	s_movk_i32 s0, 0x2800
	v_bfe_u32 v4, v75, 5, 1
	v_mad_i64_i32 v[0:1], s[0:1], v162, s0, v[0:1]
	v_lshl_add_u64 v[0:1], s[74:75], 1, v[0:1]
	v_lshlrev_b32_e32 v128, 4, v4
	v_lshl_add_u64 v[0:1], v[0:1], 0, v[128:129]
	s_mov_b64 s[0:1], 0x2400
	v_lshl_add_u64 v[2:3], v[0:1], 0, s[0:1]
	s_movk_i32 s0, 0x2000
	v_add_co_u32_e32 v0, vcc, s0, v0
	s_waitcnt lgkmcnt(0)
	s_nop 0
	v_addc_co_u32_e32 v1, vcc, 0, v1, vcc
	s_barrier
	flat_load_dwordx4 v[28:31], v[0:1] offset:1024
	flat_load_dwordx4 v[32:35], v[2:3] offset:32
	flat_load_dwordx4 v[36:39], v[2:3] offset:64
	flat_load_dwordx4 v[40:43], v[2:3] offset:96
	flat_load_dwordx4 v[44:47], v[2:3] offset:128
	flat_load_dwordx4 v[48:51], v[2:3] offset:160
	flat_load_dwordx4 v[52:55], v[2:3] offset:192
	flat_load_dwordx4 v[8:11], v[2:3] offset:224
	v_xor_b32_e32 v0, 32, v237
	v_cmp_lt_i32_e32 vcc, v0, v76
	v_lshlrev_b32_e32 v77, 5, v4
	v_lshlrev_b32_e32 v164, 3, v4
	v_cndmask_b32_e32 v0, v237, v0, vcc
	v_lshlrev_b32_e32 v167, 2, v0
	v_ashrrev_i32_e32 v163, 31, v162
	v_add_u32_e32 v128, 0, v128
	s_waitcnt vmcnt(0) lgkmcnt(0)
	v_lshlrev_b32_e32 v182, 16, v31
	v_lshlrev_b32_e32 v160, 16, v35
	v_lshlrev_b32_e32 v148, 16, v39
	v_lshlrev_b32_e32 v126, 16, v43
	v_lshlrev_b32_e32 v110, 16, v47
	v_lshlrev_b32_e32 v94, 16, v51
	v_and_b32_e32 v25, 0xffff0000, v55
	v_and_b32_e32 v17, 0xffff0000, v11
	v_and_b32_e32 v19, 0xffff0000, v10
	v_and_b32_e32 v21, 0xffff0000, v9
	v_and_b32_e32 v23, 0xffff0000, v8
	v_and_b32_e32 v27, 0xffff0000, v54
	v_lshlrev_b32_e32 v16, 16, v11
	v_lshlrev_b32_e32 v18, 16, v10
	v_mov_b32_e32 v2, v19
	v_mov_b32_e32 v3, v17
	v_lshlrev_b32_e32 v20, 16, v9
	v_lshlrev_b32_e32 v22, 16, v8
	v_mov_b32_e32 v10, v23
	v_mov_b32_e32 v11, v21
	v_lshlrev_b32_e32 v24, 16, v55
	v_lshlrev_b32_e32 v26, 16, v54
	v_mov_b32_e32 v56, v27
	v_mov_b32_e32 v57, v25
	v_mov_b32_e32 v0, v18
	v_mov_b32_e32 v1, v16
	v_pk_mul_f32 v[2:3], v[2:3], v[2:3]
	v_mov_b32_e32 v8, v22
	v_mov_b32_e32 v9, v20
	v_pk_mul_f32 v[10:11], v[10:11], v[10:11]
	v_mov_b32_e32 v54, v26
	v_mov_b32_e32 v55, v24
	v_pk_mul_f32 v[56:57], v[56:57], v[56:57]
	v_pk_fma_f32 v[80:81], v[0:1], v[0:1], v[2:3]
	global_load_dwordx4 v[0:3], v77, s[94:95] offset:464
	global_load_dwordx4 v[4:7], v77, s[94:95] offset:448
	v_pk_fma_f32 v[82:83], v[8:9], v[8:9], v[10:11]
	global_load_dwordx4 v[8:11], v77, s[94:95] offset:400
	global_load_dwordx4 v[12:15], v77, s[94:95] offset:384
	v_pk_fma_f32 v[84:85], v[54:55], v[54:55], v[56:57]
	v_lshlrev_b32_e32 v86, 16, v53
	v_and_b32_e32 v87, 0xffff0000, v53
	v_lshlrev_b32_e32 v90, 16, v52
	v_and_b32_e32 v91, 0xffff0000, v52
	v_and_b32_e32 v95, 0xffff0000, v51
	global_load_dwordx4 v[52:55], v77, s[94:95] offset:336
	global_load_dwordx4 v[56:59], v77, s[94:95] offset:320
	v_lshlrev_b32_e32 v98, 16, v50
	v_and_b32_e32 v99, 0xffff0000, v50
	v_lshlrev_b32_e32 v102, 16, v49
	v_and_b32_e32 v103, 0xffff0000, v49
	v_lshlrev_b32_e32 v106, 16, v48
	v_and_b32_e32 v107, 0xffff0000, v48
	v_and_b32_e32 v111, 0xffff0000, v47
	global_load_dwordx4 v[48:51], v77, s[94:95] offset:272
	global_load_dwordx4 v[60:63], v77, s[94:95] offset:256
	v_lshlrev_b32_e32 v114, 16, v46
	v_and_b32_e32 v115, 0xffff0000, v46
	v_lshlrev_b32_e32 v118, 16, v45
	v_and_b32_e32 v119, 0xffff0000, v45
	v_lshlrev_b32_e32 v122, 16, v44
	v_and_b32_e32 v123, 0xffff0000, v44
	v_and_b32_e32 v127, 0xffff0000, v43
	global_load_dwordx4 v[44:47], v77, s[94:95] offset:208
	global_load_dwordx4 v[64:67], v77, s[94:95] offset:192
	v_lshlrev_b32_e32 v144, 16, v42
	v_and_b32_e32 v145, 0xffff0000, v42
	v_lshlrev_b32_e32 v146, 16, v41
	v_and_b32_e32 v147, 0xffff0000, v41
	v_lshlrev_b32_e32 v142, 16, v40
	v_and_b32_e32 v143, 0xffff0000, v40
	v_and_b32_e32 v149, 0xffff0000, v39
	global_load_dwordx4 v[40:43], v77, s[94:95] offset:144
	global_load_dwordx4 v[68:71], v77, s[94:95] offset:128
	v_lshlrev_b32_e32 v140, 16, v38
	v_and_b32_e32 v141, 0xffff0000, v38
; __device__ __forceinline__ float bflo(unsigned w) { return __uint_as_float(w << 16); }
; __device__ __forceinline__ float bfhi(unsigned w) { return __uint_as_float(w & 0xffff0000u); }
; __global__ void __launch_bounds__(512, 2) mk_fwd(Args a) {
;     ...
;                         u32x4 qr[8]; float ss = 0.f;
; #pragma unroll
;                         for (int d0 = 0; d0 < 8; ++d0) { qr[d0] = *(const u32x4*)(qrow + 16 * d0);
; #pragma unroll
;                             for (int e = 0; e < 4; ++e) { const float lo = bflo(qr[d0][e]), hh = bfhi(qr[d0][e]); ss += lo * lo + hh * hh; } }
;                         ss += __shfl_xor(ss, 32);
;                         const float rstd = 1.0f / sqrtf(ss * (1.0f / 128.0f) + 1e-6f);
	v_lshlrev_b32_e32 v152, 16, v37
	v_and_b32_e32 v153, 0xffff0000, v37
	v_lshlrev_b32_e32 v156, 16, v36
	v_and_b32_e32 v157, 0xffff0000, v36
	v_and_b32_e32 v161, 0xffff0000, v35
	global_load_dwordx4 v[36:39], v77, s[94:95] offset:80
	global_load_dwordx4 v[72:75], v77, s[94:95] offset:64
	v_lshlrev_b32_e32 v170, 16, v34
	v_and_b32_e32 v171, 0xffff0000, v34
	v_lshlrev_b32_e32 v174, 16, v33
	v_and_b32_e32 v175, 0xffff0000, v33
	v_lshlrev_b32_e32 v178, 16, v32
	v_and_b32_e32 v179, 0xffff0000, v32
	global_load_dwordx4 v[32:35], v77, s[94:95] offset:16
	s_nop 0
	global_load_dwordx4 v[76:79], v77, s[94:95]
	v_and_b32_e32 v183, 0xffff0000, v31
	v_lshlrev_b32_e32 v188, 16, v29
	v_and_b32_e32 v189, 0xffff0000, v29
	v_lshlrev_b32_e32 v192, 16, v28
	v_and_b32_e32 v193, 0xffff0000, v28
	v_pk_mul_f32 v[184:185], v[182:183], v[182:183]
	v_lshlrev_b32_e32 v186, 16, v30
	v_and_b32_e32 v187, 0xffff0000, v30
	v_pk_mul_f32 v[190:191], v[188:189], v[188:189]
	v_pk_mul_f32 v[28:29], v[192:193], v[192:193]
	v_pk_mul_f32 v[30:31], v[186:187], v[186:187]
	v_add_f32_e32 v184, v184, v185
	v_add_f32_e32 v185, v190, v191
	v_add_f32_e32 v28, v28, v29
	v_add_f32_e32 v28, v28, v185
	v_add_f32_e32 v29, v30, v31
	v_pk_mul_f32 v[180:181], v[178:179], v[178:179]
	v_add_f32_e32 v28, v28, v29
	v_pk_mul_f32 v[176:177], v[174:175], v[174:175]
	v_add_f32_e32 v28, v28, v184
	v_add_f32_e32 v29, v180, v181
	v_pk_mul_f32 v[172:173], v[170:171], v[170:171]
	v_add_f32_e32 v28, v28, v29
	v_add_f32_e32 v29, v176, v177
	v_pk_mul_f32 v[168:169], v[160:161], v[160:161]
	v_add_f32_e32 v28, v28, v29
	v_add_f32_e32 v29, v172, v173
	v_pk_mul_f32 v[158:159], v[156:157], v[156:157]
	v_add_f32_e32 v28, v28, v29
	v_add_f32_e32 v29, v168, v169
	v_pk_mul_f32 v[154:155], v[152:153], v[152:153]
	v_add_f32_e32 v28, v28, v29
	v_add_f32_e32 v29, v158, v159
	v_pk_mul_f32 v[150:151], v[140:141], v[140:141]
	v_add_f32_e32 v28, v28, v29
	v_add_f32_e32 v29, v154, v155
	v_pk_mul_f32 v[138:139], v[148:149], v[148:149]
	v_add_f32_e32 v28, v28, v29
	v_add_f32_e32 v29, v150, v151
	v_pk_mul_f32 v[136:137], v[142:143], v[142:143]
	v_add_f32_e32 v28, v28, v29
	v_add_f32_e32 v29, v138, v139
	v_pk_mul_f32 v[134:135], v[146:147], v[146:147]
	v_add_f32_e32 v28, v28, v29
	v_add_f32_e32 v29, v136, v137
	v_pk_mul_f32 v[132:133], v[144:145], v[144:145]
	v_add_f32_e32 v28, v28, v29
	v_add_f32_e32 v29, v134, v135
	v_pk_mul_f32 v[130:131], v[126:127], v[126:127]
	v_add_f32_e32 v28, v28, v29
	v_add_f32_e32 v29, v132, v133
	v_pk_mul_f32 v[124:125], v[122:123], v[122:123]
	v_add_f32_e32 v28, v28, v29
	v_add_f32_e32 v29, v130, v131
	v_pk_mul_f32 v[120:121], v[118:119], v[118:119]
	v_add_f32_e32 v28, v28, v29
	v_add_f32_e32 v29, v124, v125
	v_pk_mul_f32 v[116:117], v[114:115], v[114:115]
	v_add_f32_e32 v28, v28, v29
	v_add_f32_e32 v29, v120, v121
	v_pk_mul_f32 v[112:113], v[110:111], v[110:111]
	v_add_f32_e32 v28, v28, v29
	v_add_f32_e32 v29, v116, v117
	v_pk_mul_f32 v[108:109], v[106:107], v[106:107]
	v_add_f32_e32 v28, v28, v29
	v_add_f32_e32 v29, v112, v113
	v_pk_mul_f32 v[104:105], v[102:103], v[102:103]
	v_add_f32_e32 v28, v28, v29
	v_add_f32_e32 v29, v108, v109
	v_pk_mul_f32 v[100:101], v[98:99], v[98:99]
	v_add_f32_e32 v28, v28, v29
	v_add_f32_e32 v29, v104, v105
	v_pk_mul_f32 v[96:97], v[94:95], v[94:95]
	v_add_f32_e32 v28, v28, v29
	v_add_f32_e32 v29, v100, v101
	v_pk_mul_f32 v[92:93], v[90:91], v[90:91]
	v_add_f32_e32 v28, v28, v29
	v_add_f32_e32 v29, v96, v97
	v_pk_mul_f32 v[88:89], v[86:87], v[86:87]
	v_add_f32_e32 v28, v28, v29
	v_add_f32_e32 v29, v92, v93
	v_add_f32_e32 v28, v28, v29
	v_add_f32_e32 v29, v88, v89
	v_add_f32_e32 v28, v28, v29
	v_add_f32_e32 v28, v28, v84
	v_add_f32_e32 v28, v28, v85
	v_add_f32_e32 v28, v28, v82
	v_add_f32_e32 v28, v28, v83
	v_add_f32_e32 v28, v28, v80
	v_add_f32_e32 v28, v28, v81
	ds_bpermute_b32 v29, v167, v28
	v_mov_b32_e32 v169, 0xf149f2ca
	s_waitcnt lgkmcnt(0)
	v_add_f32_e32 v28, v28, v29
	v_fmamk_f32 v28, v28, 0x3c000000, v234
	v_cmp_gt_f32_e32 vcc, s33, v28
	v_mul_f32_e32 v29, 0x4f800000, v28
	s_nop 0
	v_cndmask_b32_e32 v28, v28, v29, vcc
	v_sqrt_f32_e32 v29, v28
	s_nop 0
	v_add_u32_e32 v30, -1, v29
	v_fma_f32 v31, -v30, v29, v28
	v_cmp_ge_f32_e64 s[6:7], 0, v31
	v_add_u32_e32 v31, 1, v29
	s_nop 0
	v_cndmask_b32_e64 v30, v29, v30, s[6:7]
	v_fma_f32 v29, -v31, v29, v28
	v_cmp_lt_f32_e64 s[6:7], 0, v29
	s_nop 1
	v_cndmask_b32_e64 v29, v30, v31, s[6:7]
	v_mul_f32_e32 v30, 0x37800000, v29
	v_cndmask_b32_e32 v29, v29, v30, vcc
	v_cmp_class_f32_e32 vcc, v28, v235
	s_nop 1
	v_cndmask_b32_e32 v28, v29, v28, vcc
	v_div_scale_f32 v29, s[0:1], v28, v28, 1.0
	v_rcp_f32_e32 v30, v29
	s_mov_b64 s[0:1], -1
	v_fma_f32 v31, -v29, v30, 1.0
	v_fmac_f32_e32 v30, v31, v30
	v_div_scale_f32 v31, vcc, 1.0, v28, 1.0
	v_mul_f32_e32 v80, v31, v30
	v_fma_f32 v81, -v29, v80, v31
	v_fmac_f32_e32 v80, v81, v30
	v_fma_f32 v29, -v29, v80, v31
	v_div_fmas_f32 v29, v29, v30, v80
	v_div_fixup_f32 v28, v29, v28, 1.0
	v_pk_mul_f32 v[30:31], v[28:29], v[192:193] op_sel_hi:[0,1]
	s_waitcnt vmcnt(0)
; __device__ __forceinline__ unsigned cvtpk(float lo, float hi) { f32x2 v = {lo, hi}; bf16x2_t b = __builtin_convertvector(v, bf16x2_t); return __builtin_bit_cast(unsigned, b); }
; __device__ __forceinline__ float bflo(unsigned w) { return __uint_as_float(w << 16); }
; __device__ __forceinline__ float bfhi(unsigned w) { return __uint_as_float(w & 0xffff0000u); }
; __global__ void __launch_bounds__(512, 2) mk_fwd(Args a) {
;     ...
;                         const float rstd = 1.0f / sqrtf(ss * (1.0f / 128.0f) + 1e-6f);
;                         bf16x8 qf[8];
; #pragma unroll
;                         for (int d0 = 0; d0 < 8; ++d0) { u32x4 o;
; #pragma unroll
;                             for (int e = 0; e < 4; ++e) o[e] = cvtpk(bflo(qr[d0][e]) * rstd * gq[16 * d0 + 2 * e], bfhi(qr[d0][e]) * rstd * gq[16 * d0 + 2 * e + 1]);
;                             qf[d0] = __builtin_bit_cast(bf16x8, o); }
;                         f32x16 O[4]; float m2, ll;
;                         attn_tile<false>(lds + LDS_KS, lds + LDS_VT, qf, 0, r32, hi, O, m2, ll);
	v_pk_mul_f32 v[30:31], v[76:77], v[30:31]
	s_nop 0
	v_cvt_pk_bf16_f32 v130, v30, v31
	v_pk_mul_f32 v[30:31], v[28:29], v[188:189] op_sel_hi:[0,1]
	v_pk_mul_f32 v[30:31], v[78:79], v[30:31]
	s_nop 0
	v_cvt_pk_bf16_f32 v131, v30, v31
	v_pk_mul_f32 v[30:31], v[28:29], v[186:187] op_sel_hi:[0,1]
	v_pk_mul_f32 v[30:31], v[32:33], v[30:31]
	v_mov_b32_e32 v32, 0
	v_cvt_pk_bf16_f32 v132, v30, v31
	v_pk_mul_f32 v[30:31], v[28:29], v[182:183] op_sel_hi:[0,1]
	v_pk_mul_f32 v[30:31], v[34:35], v[30:31]
	v_mov_b32_e32 v33, v166
	v_cvt_pk_bf16_f32 v133, v30, v31
	v_pk_mul_f32 v[30:31], v[28:29], v[178:179] op_sel_hi:[0,1]
	v_pk_mul_f32 v[30:31], v[72:73], v[30:31]
	v_mov_b32_e32 v34, v166
	v_cvt_pk_bf16_f32 v134, v30, v31
	v_pk_mul_f32 v[30:31], v[28:29], v[174:175] op_sel_hi:[0,1]
	v_pk_mul_f32 v[30:31], v[74:75], v[30:31]
	v_mov_b32_e32 v35, v166
	v_cvt_pk_bf16_f32 v135, v30, v31
	v_pk_mul_f32 v[30:31], v[28:29], v[170:171] op_sel_hi:[0,1]
	v_pk_mul_f32 v[30:31], v[36:37], v[30:31]
	v_mov_b32_e32 v36, v166
	v_cvt_pk_bf16_f32 v136, v30, v31
	v_pk_mul_f32 v[30:31], v[28:29], v[160:161] op_sel_hi:[0,1]
	v_pk_mul_f32 v[30:31], v[38:39], v[30:31]
	v_mov_b32_e32 v37, v166
	v_cvt_pk_bf16_f32 v137, v30, v31
	v_pk_mul_f32 v[30:31], v[28:29], v[156:157] op_sel_hi:[0,1]
	v_pk_mul_f32 v[30:31], v[68:69], v[30:31]
	v_mov_b32_e32 v38, v166
	v_cvt_pk_bf16_f32 v138, v30, v31
	v_pk_mul_f32 v[30:31], v[28:29], v[152:153] op_sel_hi:[0,1]
	v_pk_mul_f32 v[30:31], v[70:71], v[30:31]
	v_mov_b32_e32 v39, v166
	v_cvt_pk_bf16_f32 v139, v30, v31
	v_pk_mul_f32 v[30:31], v[28:29], v[140:141] op_sel_hi:[0,1]
	v_pk_mul_f32 v[30:31], v[40:41], v[30:31]
	v_mov_b32_e32 v40, v166
	v_cvt_pk_bf16_f32 v140, v30, v31
	v_pk_mul_f32 v[30:31], v[28:29], v[148:149] op_sel_hi:[0,1]
	v_pk_mul_f32 v[30:31], v[42:43], v[30:31]
	v_mov_b32_e32 v41, v166
	v_cvt_pk_bf16_f32 v141, v30, v31
	v_pk_mul_f32 v[30:31], v[28:29], v[142:143] op_sel_hi:[0,1]
	v_pk_mul_f32 v[30:31], v[64:65], v[30:31]
	v_mov_b32_e32 v42, v166
	v_cvt_pk_bf16_f32 v142, v30, v31
	v_pk_mul_f32 v[30:31], v[28:29], v[146:147] op_sel_hi:[0,1]
	v_pk_mul_f32 v[30:31], v[66:67], v[30:31]
	v_mov_b32_e32 v43, v166
	v_cvt_pk_bf16_f32 v143, v30, v31
	v_pk_mul_f32 v[30:31], v[28:29], v[144:145] op_sel_hi:[0,1]
	v_pk_mul_f32 v[30:31], v[44:45], v[30:31]
	v_mov_b32_e32 v44, v166
	v_cvt_pk_bf16_f32 v144, v30, v31
	v_pk_mul_f32 v[30:31], v[28:29], v[126:127] op_sel_hi:[0,1]
	v_pk_mul_f32 v[30:31], v[46:47], v[30:31]
	v_mov_b32_e32 v45, v166
	v_cvt_pk_bf16_f32 v145, v30, v31
	v_pk_mul_f32 v[30:31], v[28:29], v[122:123] op_sel_hi:[0,1]
	v_pk_mul_f32 v[30:31], v[60:61], v[30:31]
	v_mov_b32_e32 v46, v166
	v_cvt_pk_bf16_f32 v146, v30, v31
	v_pk_mul_f32 v[30:31], v[28:29], v[118:119] op_sel_hi:[0,1]
	v_pk_mul_f32 v[30:31], v[62:63], v[30:31]
	v_mov_b32_e32 v47, v166
	v_cvt_pk_bf16_f32 v147, v30, v31
	v_pk_mul_f32 v[30:31], v[28:29], v[114:115] op_sel_hi:[0,1]
	v_pk_mul_f32 v[30:31], v[48:49], v[30:31]
	v_mov_b32_e32 v48, 0
	v_cvt_pk_bf16_f32 v148, v30, v31
	v_pk_mul_f32 v[30:31], v[28:29], v[110:111] op_sel_hi:[0,1]
	v_pk_mul_f32 v[30:31], v[50:51], v[30:31]
	v_mov_b32_e32 v49, v166
	v_cvt_pk_bf16_f32 v149, v30, v31
	v_pk_mul_f32 v[30:31], v[28:29], v[106:107] op_sel_hi:[0,1]
	v_pk_mul_f32 v[30:31], v[56:57], v[30:31]
	v_mov_b32_e32 v50, v166
	v_cvt_pk_bf16_f32 v150, v30, v31
	v_pk_mul_f32 v[30:31], v[28:29], v[102:103] op_sel_hi:[0,1]
	v_pk_mul_f32 v[30:31], v[58:59], v[30:31]
	v_mov_b32_e32 v51, v166
	v_cvt_pk_bf16_f32 v151, v30, v31
	v_pk_mul_f32 v[30:31], v[28:29], v[98:99] op_sel_hi:[0,1]
	v_pk_mul_f32 v[30:31], v[52:53], v[30:31]
	v_mov_b32_e32 v52, v166
	v_cvt_pk_bf16_f32 v152, v30, v31
	v_pk_mul_f32 v[30:31], v[28:29], v[94:95] op_sel_hi:[0,1]
	v_pk_mul_f32 v[30:31], v[54:55], v[30:31]
	v_mov_b32_e32 v53, v166
	v_cvt_pk_bf16_f32 v153, v30, v31
	v_pk_mul_f32 v[30:31], v[28:29], v[90:91] op_sel_hi:[0,1]
	v_pk_mul_f32 v[12:13], v[12:13], v[30:31]
	v_mov_b32_e32 v30, v166
	v_cvt_pk_bf16_f32 v154, v12, v13
	v_pk_mul_f32 v[12:13], v[28:29], v[86:87] op_sel_hi:[0,1]
	v_pk_mul_f32 v[12:13], v[14:15], v[12:13]
	v_mov_b32_e32 v14, v166
	v_cvt_pk_bf16_f32 v155, v12, v13
	v_pk_mul_f32 v[12:13], v[28:29], v[26:27] op_sel_hi:[0,1]
	v_pk_mul_f32 v[8:9], v[8:9], v[12:13]
	v_mov_b32_e32 v12, v166
	v_cvt_pk_bf16_f32 v156, v8, v9
	v_pk_mul_f32 v[8:9], v[28:29], v[24:25] op_sel_hi:[0,1]
	v_pk_mul_f32 v[8:9], v[10:11], v[8:9]
	v_mov_b32_e32 v10, v166
	v_cvt_pk_bf16_f32 v157, v8, v9
	v_pk_mul_f32 v[8:9], v[28:29], v[22:23] op_sel_hi:[0,1]
	v_pk_mul_f32 v[4:5], v[4:5], v[8:9]
	v_mov_b32_e32 v8, v166
	v_cvt_pk_bf16_f32 v158, v4, v5
	v_pk_mul_f32 v[4:5], v[28:29], v[20:21] op_sel_hi:[0,1]
	v_pk_mul_f32 v[4:5], v[6:7], v[4:5]
	v_mov_b32_e32 v6, v166
	v_cvt_pk_bf16_f32 v159, v4, v5
	v_pk_mul_f32 v[4:5], v[28:29], v[18:19] op_sel_hi:[0,1]
	v_pk_mul_f32 v[0:1], v[0:1], v[4:5]
	v_mov_b32_e32 v4, v166
	v_cvt_pk_bf16_f32 v160, v0, v1
	v_pk_mul_f32 v[0:1], v[28:29], v[16:17] op_sel_hi:[0,1]
	v_pk_mul_f32 v[0:1], v[2:3], v[0:1]
	v_mov_b32_e32 v2, v166
	v_cvt_pk_bf16_f32 v161, v0, v1
	v_mul_u32_u24_e32 v0, 0x210, v165
	v_add3_u32 v168, s2, v164, v0
	v_mov_b32_e32 v0, 0
	v_mov_b32_e32 v1, v166
	v_mov_b32_e32 v3, v166
	v_mov_b32_e32 v5, v166
	v_mov_b32_e32 v7, v166
	v_mov_b32_e32 v9, v166
	v_mov_b32_e32 v11, v166
	v_mov_b32_e32 v13, v166
	v_mov_b32_e32 v15, v166
	v_mov_b32_e32 v16, 0
	v_mov_b32_e32 v17, v166
	v_mov_b32_e32 v18, v166
	v_mov_b32_e32 v19, v166
	v_mov_b32_e32 v20, v166
	v_mov_b32_e32 v21, v166
	v_mov_b32_e32 v22, v166
	v_mov_b32_e32 v23, v166
	v_mov_b32_e32 v24, v166
	v_mov_b32_e32 v25, v166
	v_mov_b32_e32 v26, v166
	v_mov_b32_e32 v27, v166
	v_mov_b32_e32 v28, v166
	v_mov_b32_e32 v29, v166
	v_mov_b32_e32 v31, v166
	v_mov_b32_e32 v54, v166
	v_mov_b32_e32 v55, v166
	v_mov_b32_e32 v56, v166
	v_mov_b32_e32 v57, v166
	v_mov_b32_e32 v58, v166
	v_mov_b32_e32 v59, v166
	v_mov_b32_e32 v60, v166
	v_mov_b32_e32 v61, v166
	v_mov_b32_e32 v62, v166
	v_mov_b32_e32 v63, v166
	.p2align	6

; __global__ void __launch_bounds__(512, 2) mk_fwd(Args a) {
;     ...
;             for (int it = gw; it < 2 * I_LAYER; it += NGW) {
;                 const int l = it >= I_LAYER ? 1 : 0; int r = it - l * I_LAYER;
.LBB0_606:
	s_add_i32 s14, s14, s4
	s_add_i32 s12, s12, s13
	s_cmp_gt_i32 s14, 0x9fff
	s_cbranch_scc1 .LBB0_632
	.p2align	6

; #define PG8_STAGE(bufoff, gbase, voff) do { _Pragma("unroll") for (int _i = 0; _i < 2; ++_i) \
;         __builtin_amdgcn_global_load_lds((const unsigned*)((const char*)(gbase) + (voff)[_i]), (PG8_LAS unsigned*)(lds + (bufoff) + ldsw + _i * 8192), 16, 0, 0); } while (0)
; #define PG8_WAIT_V(n) asm volatile("s_waitcnt vmcnt(" #n ")" ::: "memory")
; #define PG8_BAR __builtin_amdgcn_s_barrier()
; template <class Epi, class Sched, bool ALIGN_EPI = false, bool SP2 = false>
; __device__ __forceinline__ void gemm_phase(PG8_LAS unsigned char* lds, const Gemm g, const Sched& S, const Epi& E) {
;     ...
;     if constexpr (SP2) {
;         PG8_STAGE(PG8_SB(0, 0), cB, voffB); PG8_STAGE(PG8_SB(0, 1), cB + hstep, voffB); PG8_STAGE(PG8_SA(0, 0), cA, voffA); PG8_STAGE(PG8_SA(0, 1), cA + hstep, voffA);
;         if (wr == 1) PG8_BAR;
;         PG8_WAIT_V(2); PG8_BAR;
;         PG8_STAGE(PG8_SB(1, 0), cB + kstep, voffB); PG8_STAGE(PG8_SA(1, 0), cA + kstep, voffA); PG8_STAGE(PG8_SB(1, 1), cB + hstep + kstep, voffB);
;         PG8_WAIT_V(6); PG8_BAR;
;     } else {
;         PG8_STAGE(PG8_SB(0, 0), cB, voffB); PG8_STAGE(PG8_SA(0, 0), cA, voffA); PG8_STAGE(PG8_SB(0, 1), cB + hstep, voffB); PG8_STAGE(PG8_SA(0, 1), cA + hstep, voffA);
;         if (wr == 1) PG8_BAR;
;         PG8_WAIT_V(4); PG8_BAR;
;         PG8_STAGE(PG8_SB(1, 0), cB + kstep, voffB); PG8_STAGE(PG8_SA(1, 0), cA + kstep, voffA); PG8_STAGE(PG8_SB(1, 1), cB + hstep + kstep, voffB);
;         PG8_WAIT_V(6); PG8_BAR;
;     }
.LBB0_644:
	v_bfe_u32 v136, v14, 4, 2
	s_lshl_b32 s12, s12, 5
	v_and_b32_e32 v15, 15, v14
	v_lshlrev_b32_e32 v16, 4, v136
	v_lshlrev_b32_e32 v14, 2, v14
	s_and_b32 s19, s12, 0x60
	v_lshl_or_b32 v137, s13, 6, v15
	v_lshl_or_b32 v15, v15, 6, v16
	s_lshl_b32 s13, s13, 13
	v_and_b32_e32 v14, 32, v14
	s_lshl_b32 s12, s19, 7
	v_bitop3_b32 v138, v15, s12, v14 bitop3:0xde
	s_add_u32 s12, s4, 0x80080
	v_bitop3_b32 v16, v15, s13, v14 bitop3:0xde
	s_addc_u32 s13, s5, 0
	s_add_i32 m0, s15, 0x18000
	v_lshl_add_u64 v[6:7], v[6:7], 0, s[76:77]
	s_waitcnt vmcnt(2)
	s_barrier
	global_load_lds_dwordx4 v[6:7], off
	v_lshl_add_u64 v[4:5], v[4:5], 0, s[76:77]
	s_add_i32 m0, s15, 0x1a000
	s_add_i32 s20, s15, 0x8000
	global_load_lds_dwordx4 v[4:5], off
	v_lshl_add_u64 v[2:3], v[2:3], 0, s[76:77]
	s_mov_b32 m0, s20
	s_add_i32 s21, s15, 0xa000
	global_load_lds_dwordx4 v[2:3], off
	v_lshl_add_u64 v[0:1], v[0:1], 0, s[76:77]
	s_mov_b32 m0, s21
	s_mov_b32 s26, -2
	global_load_lds_dwordx4 v[0:1], off
	s_add_i32 m0, s15, 0x1c000
	v_lshl_add_u64 v[0:1], s[12:13], 0, v[128:129]
	global_load_lds_dwordx4 v[0:1], off
	v_lshl_add_u64 v[0:1], s[12:13], 0, v[130:131]
	s_add_i32 m0, s15, 0x1e000
	s_add_u32 s10, s80, s10
	global_load_lds_dwordx4 v[0:1], off
	s_addc_u32 s11, s81, s11
	s_add_u32 s22, s10, 0x1600100
	s_addc_u32 s23, s11, 0
	v_lshlrev_b32_e32 v0, 15, v8
	v_and_b32_e32 v0, 0xffff0000, v0
	s_add_u32 s24, s80, s8
	v_lshl_add_u32 v0, v10, 12, v0
	v_and_b32_e32 v1, 1, v8
	s_addc_u32 s25, s81, s9
	v_lshl_or_b32 v0, v1, 6, v0
	s_add_u32 s8, s24, 0xc80080
	v_lshl_add_u32 v0, v11, 1, v0
	v_mov_b32_e32 v1, v129
	s_addc_u32 s9, s25, 0
	v_lshl_add_u64 v[132:133], s[8:9], 0, v[0:1]
	v_lshlrev_b32_e32 v0, 15, v9
	v_and_b32_e32 v0, 0xffff0000, v0
	v_lshl_add_u32 v0, v12, 12, v0
	v_and_b32_e32 v1, 1, v9
	v_lshl_or_b32 v0, v1, 6, v0
	s_waitcnt vmcnt(6)
	v_lshl_add_u32 v0, v13, 1, v0
	v_mov_b32_e32 v1, v129
	v_lshl_add_u64 v[134:135], s[8:9], 0, v[0:1]
	v_mov_b32_e32 v0, 0
	s_mov_b64 s[8:9], 0
	v_add_u32_e32 v139, 0, v16
	v_mov_b32_e32 v1, v0
	v_mov_b32_e32 v2, v0
	v_mov_b32_e32 v3, v0
	v_mov_b32_e32 v4, v0
	v_mov_b32_e32 v5, v0
	v_mov_b32_e32 v6, v0
	v_mov_b32_e32 v7, v0
	v_mov_b32_e32 v8, v0
	v_mov_b32_e32 v9, v0
	v_mov_b32_e32 v10, v0
	v_mov_b32_e32 v11, v0
	v_mov_b32_e32 v12, v0
	v_mov_b32_e32 v13, v0
	v_mov_b32_e32 v14, v0
	v_mov_b32_e32 v15, v0
	v_mov_b32_e32 v24, v0
	v_mov_b32_e32 v25, v0
	v_mov_b32_e32 v26, v0
	v_mov_b32_e32 v27, v0
	v_mov_b32_e32 v28, v0
	v_mov_b32_e32 v29, v0
	v_mov_b32_e32 v30, v0
	v_mov_b32_e32 v31, v0
	v_mov_b32_e32 v40, v0
	v_mov_b32_e32 v41, v0
	v_mov_b32_e32 v42, v0
	v_mov_b32_e32 v43, v0
	v_mov_b32_e32 v44, v0
	v_mov_b32_e32 v45, v0
	v_mov_b32_e32 v46, v0
	v_mov_b32_e32 v47, v0
	v_mov_b32_e32 v16, v0
	v_mov_b32_e32 v17, v0
	v_mov_b32_e32 v18, v0
	v_mov_b32_e32 v19, v0
	v_mov_b32_e32 v20, v0
	v_mov_b32_e32 v21, v0
	v_mov_b32_e32 v22, v0
	v_mov_b32_e32 v23, v0
	v_mov_b32_e32 v32, v0
	v_mov_b32_e32 v33, v0
	v_mov_b32_e32 v34, v0
	v_mov_b32_e32 v35, v0
	v_mov_b32_e32 v36, v0
	v_mov_b32_e32 v37, v0
	v_mov_b32_e32 v38, v0
	v_mov_b32_e32 v39, v0
	v_mov_b32_e32 v48, v0
	v_mov_b32_e32 v49, v0
	v_mov_b32_e32 v50, v0
	v_mov_b32_e32 v51, v0
	v_mov_b32_e32 v52, v0
	v_mov_b32_e32 v53, v0
	v_mov_b32_e32 v54, v0
	v_mov_b32_e32 v55, v0
	v_mov_b32_e32 v56, v0
	v_mov_b32_e32 v57, v0
	v_mov_b32_e32 v58, v0
	v_mov_b32_e32 v59, v0
	v_mov_b32_e32 v60, v0
	v_mov_b32_e32 v61, v0
	v_mov_b32_e32 v62, v0
	v_mov_b32_e32 v63, v0
	v_mov_b32_e32 v64, v0
	v_mov_b32_e32 v65, v0
	v_mov_b32_e32 v66, v0
	v_mov_b32_e32 v67, v0
	v_mov_b32_e32 v68, v0
	v_mov_b32_e32 v69, v0
	v_mov_b32_e32 v70, v0
	v_mov_b32_e32 v71, v0
	v_mov_b32_e32 v72, v0
	v_mov_b32_e32 v73, v0
	v_mov_b32_e32 v74, v0
	v_mov_b32_e32 v75, v0
	v_mov_b32_e32 v76, v0
	v_mov_b32_e32 v77, v0
	v_mov_b32_e32 v78, v0
	v_mov_b32_e32 v79, v0
	v_mov_b32_e32 v84, v0
	v_mov_b32_e32 v85, v0
	v_mov_b32_e32 v86, v0
	v_mov_b32_e32 v87, v0
	v_mov_b32_e32 v92, v0
	v_mov_b32_e32 v93, v0
	v_mov_b32_e32 v94, v0
	v_mov_b32_e32 v95, v0
	v_mov_b32_e32 v100, v0
	v_mov_b32_e32 v101, v0
	v_mov_b32_e32 v102, v0
	v_mov_b32_e32 v103, v0
	v_mov_b32_e32 v108, v0
	v_mov_b32_e32 v109, v0
	v_mov_b32_e32 v110, v0
	v_mov_b32_e32 v111, v0
	v_mov_b32_e32 v80, v0
	v_mov_b32_e32 v81, v0
	v_mov_b32_e32 v82, v0
	v_mov_b32_e32 v83, v0
	v_mov_b32_e32 v88, v0
	v_mov_b32_e32 v89, v0
	v_mov_b32_e32 v90, v0
	v_mov_b32_e32 v91, v0
	v_mov_b32_e32 v96, v0
	v_mov_b32_e32 v97, v0
	v_mov_b32_e32 v98, v0
	v_mov_b32_e32 v99, v0
	v_mov_b32_e32 v104, v0
	v_mov_b32_e32 v105, v0
	v_mov_b32_e32 v106, v0
	v_mov_b32_e32 v107, v0
	v_mov_b32_e32 v112, v0
	v_mov_b32_e32 v113, v0
	v_mov_b32_e32 v114, v0
	v_mov_b32_e32 v115, v0
	v_mov_b32_e32 v116, v0
	v_mov_b32_e32 v117, v0
	v_mov_b32_e32 v118, v0
	v_mov_b32_e32 v119, v0
	v_mov_b32_e32 v120, v0
	v_mov_b32_e32 v121, v0
	v_mov_b32_e32 v122, v0
	v_mov_b32_e32 v123, v0
	v_mov_b32_e32 v124, v0
	v_mov_b32_e32 v125, v0
	v_mov_b32_e32 v126, v0
	v_mov_b32_e32 v127, v0
	s_barrier
	.p2align	6
